# census loads in parallel; K-loops first iteration peeled with SrcC=0 (no accumulator zeroing); drop unit-start vmcnt(0) in FFN-up
# speedup vs baseline: 1.0071x; 1.0071x over previous
; #define PG8_STAGE(bufoff, gbase, voff) do { _Pragma("unroll") for (int _i = 0; _i < 2; ++_i) \
;         __builtin_amdgcn_global_load_lds((const unsigned*)((const char*)(gbase) + (voff)[_i]), (PG8_LAS unsigned*)(lds + (bufoff) + ldsw + _i * 8192), 16, 0, 0); } while (0)
; #define PG8_LDA(dst, b, h) do { _Pragma("unroll") for (int m = 0; m < 4; ++m) _Pragma("unroll") for (int k = 0; k < 2; ++k) dst[m][k] = *(const PG8_LAS bf16x8*)(lds + PG8_SA(b, h) + aoff + m * 2048 + k * 1024); } while (0)
; #define PG8_LDB(dst, b, h) do { _Pragma("unroll") for (int n = 0; n < 2; ++n) _Pragma("unroll") for (int k = 0; k < 2; ++k) dst[n][k] = *(const PG8_LAS bf16x8*)(lds + PG8_SB(b, h) + boff + n * 2048 + k * 1024); } while (0)
; #define PG8_MMA(ai, bj, At, Bt) do { __builtin_amdgcn_s_setprio(1); _Pragma("unroll") for (int m = 0; m < 4; ++m) _Pragma("unroll") for (int n = 0; n < 2; ++n) _Pragma("unroll") for (int k = 0; k < 2; ++k) \
;         acc[ai][bj][m][n] = mma16<Epi::I8>(Bt[n][k], At[m][k], acc[ai][bj][m][n]); __builtin_amdgcn_s_setprio(0); } while (0)
; template <class Epi, class Sched, bool ALIGN_EPI = false, bool SP2 = false>
; __device__ __forceinline__ void gemm_phase(PG8_LAS unsigned char* lds, const Gemm g, const Sched& S, const Epi& E) {
;     ...
;         const bool has_next = S.next(ui + 1, nxt);
;         const char* nA = has_next ? (const char*)g.A + (size_t)nxt.pm * tstep : cA; const char* nB = has_next ? (const char*)g.Bt + (size_t)nxt.pn * tstep : cB;
;         for (int t = 0; t < nt; t += 2) {
;     ...
;             PG8_LDB(B0, 0, 0); PG8_LDB(B1, 0, 1); PG8_SCHED; PG8_LDA(At, 0, 0); PG8_STAGE(PG8_SA(1, 1), a1 + hstep, voffA);
;             PG8_WAIT_V(8); PG8_WAIT_L(0); PG8_BAR; PG8_MMA(0, 0, At, B0); PG8_MMA(0, 1, At, B1); PG8_BAR; PG8_SCHED;
;             PG8_LDA(At, 0, 1); PG8_STAGE(PG8_SB(0, 0), b2, voffB); PG8_STAGE(PG8_SB(0, 1), b2 + hstep, voffB); PG8_STAGE(PG8_SA(0, 0), a2, voffA);
;             PG8_WAIT_V(8); PG8_WAIT_L(0); PG8_BAR; PG8_MMA(1, 0, At, B0); PG8_MMA(1, 1, At, B1); PG8_BAR; PG8_SCHED;
;     ...
; #pragma unroll
;         for (int a = 0; a < 2; ++a)
; #pragma unroll
;             for (int b = 0; b < 2; ++b)
; #pragma unroll
;                 for (int m = 0; m < 4; ++m)
; #pragma unroll
;                     for (int n = 0; n < 2; ++n) acc[a][b][m][n] = (f32x4){0.f, 0.f, 0.f, 0.f};
;         cur = nxt; cA = nA; cB = nB; ++ui;
.LBB0_79:
	s_ashr_i32 s13, s12, 31
	s_lshl_b64 s[6:7], s[12:13], 19
	v_readlane_b32 s4, v252, 41
	s_mov_b32 s38, s12
	v_readlane_b32 s5, v252, 42
	s_add_u32 s4, s4, s6
	v_readlane_b32 s12, v254, 42
	s_addc_u32 s5, s5, s7
	v_readlane_b32 s13, v254, 43
	s_and_b64 s[6:7], s[12:13], exec
	s_cselect_b32 s66, s5, s1
	v_writelane_b32 v254, s4, 50
	s_cselect_b32 s67, s4, s0
	v_writelane_b32 v254, s5, 51
	s_mov_b32 s4, s40
	s_ashr_i32 s5, s40, 31
	s_lshl_b64 s[6:7], s[4:5], 19
	v_readlane_b32 s4, v254, 56
	s_add_u32 s96, s4, s6
	v_readlane_b32 s4, v254, 57
	s_addc_u32 s97, s4, s7
	s_and_b64 s[6:7], s[12:13], exec
	s_cselect_b32 s82, s97, s9
	v_writelane_b32 v254, s96, 48
	s_cselect_b32 s83, s96, s8
	s_mov_b32 vcc_lo, -2
	v_writelane_b32 v254, s97, 49
	s_add_u32 s96, s8, 0x100
	s_addc_u32 s97, s9, 0
.Lpeel80:
	s_add_u32 s8, s0, 0x100
	s_addc_u32 s9, s1, 0
	s_add_i32 vcc_hi, 0, 0x10000
	s_cmp_eq_u32 vcc_lo, 12
	s_cselect_b32 s13, s66, s9
	s_cselect_b32 s12, s67, s8
	s_cselect_b32 s7, s82, s97
	s_cselect_b32 s6, s83, s96
	s_add_i32 s4, 0, 0x14000
	v_add_u32_e32 v38, vcc_hi, v242
	v_add_u32_e32 v158, s4, v242
	ds_read_b128 v[18:21], v38
	ds_read_b128 v[22:25], v38 offset:1024
	ds_read_b128 v[34:37], v38 offset:2048
	ds_read_b128 v[38:41], v38 offset:3072
	ds_read_b128 v[130:133], v158
	ds_read_b128 v[134:137], v158 offset:1024
	ds_read_b128 v[154:157], v158 offset:2048
	ds_read_b128 v[158:161], v158 offset:3072
	v_lshl_add_u64 v[194:195], s[0:1], 0, v[216:217]
	s_add_i32 m0, s11, 0xc000
	ds_read_b128 v[162:165], v243
	ds_read_b128 v[166:169], v243 offset:1024
	ds_read_b128 v[170:173], v243 offset:2048
	ds_read_b128 v[174:177], v243 offset:3072
	ds_read_b128 v[178:181], v243 offset:4096
	ds_read_b128 v[182:185], v243 offset:5120
	ds_read_b128 v[186:189], v243 offset:6144
	ds_read_b128 v[190:193], v243 offset:7168
	global_load_lds_dwordx4 v[194:195], off
	v_lshl_add_u64 v[194:195], s[0:1], 0, v[218:219]
	s_add_i32 m0, s11, 0xe000
	s_nop 0
	global_load_lds_dwordx4 v[194:195], off
	s_waitcnt vmcnt(8)
	s_waitcnt lgkmcnt(0)
	s_barrier
	s_setprio 1
	s_waitcnt lgkmcnt(0)
	v_mfma_i32_16x16x64_i8 v[150:153], v[18:21], v[162:165], 0
	v_mfma_i32_16x16x64_i8 v[146:149], v[34:37], v[162:165], 0
	v_mfma_i32_16x16x64_i8 v[118:121], v[18:21], v[170:173], 0
	v_mfma_i32_16x16x64_i8 v[110:113], v[34:37], v[170:173], 0
	v_mfma_i32_16x16x64_i8 v[54:57], v[18:21], v[178:181], 0
	v_mfma_i32_16x16x64_i8 v[30:33], v[34:37], v[178:181], 0
	v_mfma_i32_16x16x64_i8 v[94:97], v[18:21], v[186:189], 0
	v_mfma_i32_16x16x64_i8 v[58:61], v[34:37], v[186:189], 0
	v_mfma_i32_16x16x64_i8 v[150:153], v[22:25], v[166:169], v[150:153]
	v_mfma_i32_16x16x64_i8 v[146:149], v[38:41], v[166:169], v[146:149]
	v_mfma_i32_16x16x64_i8 v[118:121], v[22:25], v[174:177], v[118:121]
	v_mfma_i32_16x16x64_i8 v[110:113], v[38:41], v[174:177], v[110:113]
	v_mfma_i32_16x16x64_i8 v[54:57], v[22:25], v[182:185], v[54:57]
	v_mfma_i32_16x16x64_i8 v[30:33], v[38:41], v[182:185], v[30:33]
	v_mfma_i32_16x16x64_i8 v[94:97], v[22:25], v[190:193], v[94:97]
	v_mfma_i32_16x16x64_i8 v[58:61], v[38:41], v[190:193], v[58:61]
	s_setprio 0
	s_setprio 1
	v_mfma_i32_16x16x64_i8 v[142:145], v[130:133], v[162:165], 0
	v_mfma_i32_16x16x64_i8 v[138:141], v[154:157], v[162:165], 0
	v_mfma_i32_16x16x64_i8 v[102:105], v[130:133], v[170:173], 0
	v_mfma_i32_16x16x64_i8 v[98:101], v[154:157], v[170:173], 0
	v_mfma_i32_16x16x64_i8 v[42:45], v[130:133], v[178:181], 0
	v_mfma_i32_16x16x64_i8 v[26:29], v[154:157], v[178:181], 0
	v_mfma_i32_16x16x64_i8 v[78:81], v[130:133], v[186:189], 0
	v_mfma_i32_16x16x64_i8 v[62:65], v[154:157], v[186:189], 0
	v_mfma_i32_16x16x64_i8 v[142:145], v[134:137], v[166:169], v[142:145]
	v_mfma_i32_16x16x64_i8 v[138:141], v[158:161], v[166:169], v[138:141]
	v_mfma_i32_16x16x64_i8 v[102:105], v[134:137], v[174:177], v[102:105]
	v_mfma_i32_16x16x64_i8 v[98:101], v[158:161], v[174:177], v[98:101]
	v_mfma_i32_16x16x64_i8 v[42:45], v[134:137], v[182:185], v[42:45]
	v_mfma_i32_16x16x64_i8 v[26:29], v[158:161], v[182:185], v[26:29]
	v_mfma_i32_16x16x64_i8 v[78:81], v[134:137], v[190:193], v[78:81]
	v_mfma_i32_16x16x64_i8 v[62:65], v[158:161], v[190:193], v[62:65]
	s_setprio 0
	s_barrier
	s_add_i32 s0, vcc_hi, s69
	v_lshl_add_u64 v[198:199], s[6:7], 0, v[0:1]
	s_mov_b32 m0, s0
	ds_read_b128 v[162:165], v243 offset:16384
	ds_read_b128 v[166:169], v243 offset:17408
	ds_read_b128 v[170:173], v243 offset:18432
	ds_read_b128 v[174:177], v243 offset:19456
	ds_read_b128 v[178:181], v243 offset:20480
	ds_read_b128 v[182:185], v243 offset:21504
	ds_read_b128 v[186:189], v243 offset:22528
	ds_read_b128 v[190:193], v243 offset:23552
	global_load_lds_dwordx4 v[198:199], off
	s_add_i32 m0, s0, 0x2000
	s_add_u32 s0, s6, 0x40000
	v_lshl_add_u64 v[200:201], s[6:7], 0, v[214:215]
	s_addc_u32 s1, s7, 0
	s_add_i32 s4, s4, s69
	global_load_lds_dwordx4 v[200:201], off
	v_lshl_add_u64 v[194:195], s[0:1], 0, v[0:1]
	s_mov_b32 m0, s4
	v_lshl_add_u64 v[206:207], s[12:13], 0, v[210:211]
	global_load_lds_dwordx4 v[194:195], off
	v_lshl_add_u64 v[194:195], s[0:1], 0, v[214:215]
	s_add_i32 m0, s4, 0x2000
	v_lshl_add_u64 v[220:221], s[12:13], 0, v[212:213]
	global_load_lds_dwordx4 v[194:195], off
	s_mov_b32 m0, s11
	s_nop 0
	global_load_lds_dwordx4 v[206:207], off
	s_mov_b32 m0, s71
	s_nop 0
	global_load_lds_dwordx4 v[220:221], off
	s_waitcnt vmcnt(8)
	s_waitcnt lgkmcnt(0)
	s_barrier
; #define PG8_STAGE(bufoff, gbase, voff) do { _Pragma("unroll") for (int _i = 0; _i < 2; ++_i) \
;         __builtin_amdgcn_global_load_lds((const unsigned*)((const char*)(gbase) + (voff)[_i]), (PG8_LAS unsigned*)(lds + (bufoff) + ldsw + _i * 8192), 16, 0, 0); } while (0)
; #define PG8_LDA(dst, b, h) do { _Pragma("unroll") for (int m = 0; m < 4; ++m) _Pragma("unroll") for (int k = 0; k < 2; ++k) dst[m][k] = *(const PG8_LAS bf16x8*)(lds + PG8_SA(b, h) + aoff + m * 2048 + k * 1024); } while (0)
; #define PG8_LDB(dst, b, h) do { _Pragma("unroll") for (int n = 0; n < 2; ++n) _Pragma("unroll") for (int k = 0; k < 2; ++k) dst[n][k] = *(const PG8_LAS bf16x8*)(lds + PG8_SB(b, h) + boff + n * 2048 + k * 1024); } while (0)
; #define PG8_MMA(ai, bj, At, Bt) do { __builtin_amdgcn_s_setprio(1); _Pragma("unroll") for (int m = 0; m < 4; ++m) _Pragma("unroll") for (int n = 0; n < 2; ++n) _Pragma("unroll") for (int k = 0; k < 2; ++k) \
;         acc[ai][bj][m][n] = mma16<Epi::I8>(Bt[n][k], At[m][k], acc[ai][bj][m][n]); __builtin_amdgcn_s_setprio(0); } while (0)
; #define PG8_WAIT_V(n) asm volatile("s_waitcnt vmcnt(" #n ")" ::: "memory")
; #define PG8_WAIT_L(n) asm volatile("s_waitcnt lgkmcnt(" #n ")" ::: "memory")
; #define PG8_BAR __builtin_amdgcn_s_barrier()
; #define PG8_SCHED __builtin_amdgcn_sched_barrier(0)
; template <class Epi, class Sched, bool ALIGN_EPI = false, bool SP2 = false>
; __device__ __forceinline__ void gemm_phase(PG8_LAS unsigned char* lds, const Gemm g, const Sched& S, const Epi& E) {
;     ...
;             PG8_WAIT_V(8); PG8_WAIT_L(0); PG8_BAR; PG8_MMA(1, 0, At, B0); PG8_MMA(1, 1, At, B1); PG8_BAR; PG8_SCHED;
;             PG8_LDB(B0, 1, 0); PG8_LDB(B1, 1, 1); PG8_SCHED; PG8_LDA(At, 1, 0); PG8_STAGE(PG8_SA(0, 1), a2 + hstep, voffA);
;             PG8_WAIT_V(8); PG8_WAIT_L(0); PG8_BAR; PG8_MMA(0, 0, At, B0); PG8_MMA(0, 1, At, B1); PG8_BAR; PG8_SCHED;
	s_setprio 1
	s_waitcnt lgkmcnt(0)
	v_mfma_i32_16x16x64_i8 v[106:109], v[18:21], v[162:165], 0
	v_mfma_i32_16x16x64_i8 v[46:49], v[34:37], v[162:165], 0
	v_mfma_i32_16x16x64_i8 v[14:17], v[18:21], v[170:173], 0
	v_mfma_i32_16x16x64_i8 v[6:9], v[34:37], v[170:173], 0
	v_mfma_i32_16x16x64_i8 v[90:93], v[18:21], v[178:181], 0
	v_mfma_i32_16x16x64_i8 v[86:89], v[34:37], v[178:181], 0
	v_mfma_i32_16x16x64_i8 v[18:21], v[18:21], v[186:189], 0
	v_mfma_i32_16x16x64_i8 v[106:109], v[22:25], v[166:169], v[106:109]
	v_mfma_i32_16x16x64_i8 v[46:49], v[38:41], v[166:169], v[46:49]
	v_mfma_i32_16x16x64_i8 v[14:17], v[22:25], v[174:177], v[14:17]
	v_mfma_i32_16x16x64_i8 v[6:9], v[38:41], v[174:177], v[6:9]
	v_mfma_i32_16x16x64_i8 v[90:93], v[22:25], v[182:185], v[90:93]
	v_mfma_i32_16x16x64_i8 v[86:89], v[38:41], v[182:185], v[86:89]
	v_mfma_i32_16x16x64_i8 v[18:21], v[22:25], v[190:193], v[18:21]
	v_mfma_i32_16x16x64_i8 v[22:25], v[34:37], v[186:189], 0
	v_mfma_i32_16x16x64_i8 v[22:25], v[38:41], v[190:193], v[22:25]
	s_setprio 0
	s_setprio 1
	v_mfma_i32_16x16x64_i8 v[38:41], v[154:157], v[162:165], 0
	v_mfma_i32_16x16x64_i8 v[50:53], v[130:133], v[178:181], 0
	v_mfma_i32_16x16x64_i8 v[82:85], v[134:137], v[182:185], v[50:53]
	v_mfma_i32_16x16x64_i8 v[50:53], v[154:157], v[178:181], 0
	v_mfma_i32_16x16x64_i8 v[74:77], v[158:161], v[182:185], v[50:53]
	v_mfma_i32_16x16x64_i8 v[50:53], v[130:133], v[186:189], 0
	v_mfma_i32_16x16x64_i8 v[10:13], v[130:133], v[170:173], 0
	v_mfma_i32_16x16x64_i8 v[2:5], v[154:157], v[170:173], 0
	v_mfma_i32_16x16x64_i8 v[122:125], v[134:137], v[190:193], v[50:53]
	v_mfma_i32_16x16x64_i8 v[50:53], v[154:157], v[186:189], 0
	v_mfma_i32_16x16x64_i8 v[34:37], v[130:133], v[162:165], 0
	v_mfma_i32_16x16x64_i8 v[10:13], v[134:137], v[174:177], v[10:13]
	v_mfma_i32_16x16x64_i8 v[2:5], v[158:161], v[174:177], v[2:5]
	v_mfma_i32_16x16x64_i8 v[70:73], v[158:161], v[190:193], v[50:53]
	v_mfma_i32_16x16x64_i8 v[34:37], v[134:137], v[166:169], v[34:37]
	v_mfma_i32_16x16x64_i8 v[38:41], v[158:161], v[166:169], v[38:41]
	s_setprio 0
	s_barrier
	s_add_i32 s4, 0, 0x18000
	v_add_u32_e32 v126, s4, v242
	s_add_i32 s5, 0, 0x1c000
	ds_read_b128 v[50:53], v126
	ds_read_b128 v[66:69], v126 offset:1024
	ds_read_b128 v[114:117], v126 offset:2048
	ds_read_b128 v[130:133], v126 offset:3072
	v_add_u32_e32 v126, s5, v242
	ds_read_b128 v[134:137], v126
	ds_read_b128 v[154:157], v126 offset:1024
	ds_read_b128 v[158:161], v126 offset:2048
	ds_read_b128 v[162:165], v126 offset:3072
	s_add_u32 s0, s12, 0x40000
	s_addc_u32 s1, s13, 0
	s_mov_b32 m0, s80
	v_lshl_add_u64 v[194:195], s[0:1], 0, v[210:211]
	ds_read_b128 v[126:129], v243 offset:32768
	ds_read_b128 v[166:169], v243 offset:33792
	ds_read_b128 v[170:173], v243 offset:34816
	ds_read_b128 v[174:177], v243 offset:35840
	ds_read_b128 v[178:181], v243 offset:36864
	ds_read_b128 v[182:185], v243 offset:37888
	ds_read_b128 v[186:189], v243 offset:38912
	ds_read_b128 v[190:193], v243 offset:39936
	global_load_lds_dwordx4 v[194:195], off
	v_lshl_add_u64 v[194:195], s[0:1], 0, v[212:213]
	s_mov_b32 m0, s81
	s_nop 0
	global_load_lds_dwordx4 v[194:195], off
	s_waitcnt vmcnt(8)
	s_waitcnt lgkmcnt(0)
	s_barrier
	s_setprio 1
	s_waitcnt lgkmcnt(0)
	v_mfma_i32_16x16x64_i8 v[150:153], v[50:53], v[126:129], v[150:153]
	v_mfma_i32_16x16x64_i8 v[146:149], v[114:117], v[126:129], v[146:149]
	v_mfma_i32_16x16x64_i8 v[118:121], v[50:53], v[170:173], v[118:121]
	v_mfma_i32_16x16x64_i8 v[110:113], v[114:117], v[170:173], v[110:113]
	v_mfma_i32_16x16x64_i8 v[54:57], v[50:53], v[178:181], v[54:57]
	v_mfma_i32_16x16x64_i8 v[30:33], v[114:117], v[178:181], v[30:33]
	v_mfma_i32_16x16x64_i8 v[94:97], v[50:53], v[186:189], v[94:97]
	v_mfma_i32_16x16x64_i8 v[58:61], v[114:117], v[186:189], v[58:61]
	v_mfma_i32_16x16x64_i8 v[150:153], v[66:69], v[166:169], v[150:153]
	v_mfma_i32_16x16x64_i8 v[146:149], v[130:133], v[166:169], v[146:149]
	v_mfma_i32_16x16x64_i8 v[118:121], v[66:69], v[174:177], v[118:121]
	v_mfma_i32_16x16x64_i8 v[110:113], v[130:133], v[174:177], v[110:113]
	v_mfma_i32_16x16x64_i8 v[54:57], v[66:69], v[182:185], v[54:57]
	v_mfma_i32_16x16x64_i8 v[30:33], v[130:133], v[182:185], v[30:33]
	v_mfma_i32_16x16x64_i8 v[94:97], v[66:69], v[190:193], v[94:97]
	v_mfma_i32_16x16x64_i8 v[58:61], v[130:133], v[190:193], v[58:61]
	s_setprio 0
	s_setprio 1
	v_mfma_i32_16x16x64_i8 v[142:145], v[134:137], v[126:129], v[142:145]
	v_mfma_i32_16x16x64_i8 v[126:129], v[158:161], v[126:129], v[138:141]
	v_mfma_i32_16x16x64_i8 v[102:105], v[134:137], v[170:173], v[102:105]
	v_mfma_i32_16x16x64_i8 v[98:101], v[158:161], v[170:173], v[98:101]
	v_mfma_i32_16x16x64_i8 v[42:45], v[134:137], v[178:181], v[42:45]
	v_mfma_i32_16x16x64_i8 v[26:29], v[158:161], v[178:181], v[26:29]
	v_mfma_i32_16x16x64_i8 v[78:81], v[134:137], v[186:189], v[78:81]
	v_mfma_i32_16x16x64_i8 v[62:65], v[158:161], v[186:189], v[62:65]
	v_mfma_i32_16x16x64_i8 v[142:145], v[154:157], v[166:169], v[142:145]
	v_mfma_i32_16x16x64_i8 v[138:141], v[162:165], v[166:169], v[126:129]
	v_mfma_i32_16x16x64_i8 v[102:105], v[154:157], v[174:177], v[102:105]
	v_mfma_i32_16x16x64_i8 v[98:101], v[162:165], v[174:177], v[98:101]
	v_mfma_i32_16x16x64_i8 v[42:45], v[154:157], v[182:185], v[42:45]
	v_mfma_i32_16x16x64_i8 v[26:29], v[162:165], v[182:185], v[26:29]
	v_mfma_i32_16x16x64_i8 v[78:81], v[154:157], v[190:193], v[78:81]
	v_mfma_i32_16x16x64_i8 v[62:65], v[162:165], v[190:193], v[62:65]
	s_setprio 0
	s_barrier
; #define PG8_STAGE(bufoff, gbase, voff) do { _Pragma("unroll") for (int _i = 0; _i < 2; ++_i) \
;         __builtin_amdgcn_global_load_lds((const unsigned*)((const char*)(gbase) + (voff)[_i]), (PG8_LAS unsigned*)(lds + (bufoff) + ldsw + _i * 8192), 16, 0, 0); } while (0)
; #define PG8_LDA(dst, b, h) do { _Pragma("unroll") for (int m = 0; m < 4; ++m) _Pragma("unroll") for (int k = 0; k < 2; ++k) dst[m][k] = *(const PG8_LAS bf16x8*)(lds + PG8_SA(b, h) + aoff + m * 2048 + k * 1024); } while (0)
; #define PG8_MMA(ai, bj, At, Bt) do { __builtin_amdgcn_s_setprio(1); _Pragma("unroll") for (int m = 0; m < 4; ++m) _Pragma("unroll") for (int n = 0; n < 2; ++n) _Pragma("unroll") for (int k = 0; k < 2; ++k) \
;         acc[ai][bj][m][n] = mma16<Epi::I8>(Bt[n][k], At[m][k], acc[ai][bj][m][n]); __builtin_amdgcn_s_setprio(0); } while (0)
; #define PG8_WAIT_V(n) asm volatile("s_waitcnt vmcnt(" #n ")" ::: "memory")
; #define PG8_WAIT_L(n) asm volatile("s_waitcnt lgkmcnt(" #n ")" ::: "memory")
; #define PG8_BAR __builtin_amdgcn_s_barrier()
; #define PG8_SCHED __builtin_amdgcn_sched_barrier(0)
; template <class Epi, class Sched, bool ALIGN_EPI = false, bool SP2 = false>
; __device__ __forceinline__ void gemm_phase(PG8_LAS unsigned char* lds, const Gemm g, const Sched& S, const Epi& E) {
;     ...
;         for (int t = 0; t < nt; t += 2) {
;     ...
;             PG8_LDA(At, 1, 1); PG8_STAGE(PG8_SB(1, 0), b3, voffB); PG8_STAGE(PG8_SB(1, 1), b3 + hstep, voffB); PG8_STAGE(PG8_SA(1, 0), a3, voffA);
;             PG8_WAIT_V(8); PG8_WAIT_L(0); PG8_BAR; PG8_MMA(1, 0, At, B0); PG8_MMA(1, 1, At, B1); PG8_BAR; PG8_SCHED;
	s_add_i32 s0, s4, s69
	v_lshl_add_u64 v[126:127], v[198:199], 0, s[92:93]
	s_mov_b32 m0, s0
	ds_read_b128 v[166:169], v243 offset:49152
	ds_read_b128 v[170:173], v243 offset:50176
	ds_read_b128 v[174:177], v243 offset:51200
	ds_read_b128 v[178:181], v243 offset:52224
	ds_read_b128 v[182:185], v243 offset:53248
	ds_read_b128 v[186:189], v243 offset:54272
	ds_read_b128 v[190:193], v243 offset:55296
	ds_read_b128 v[194:197], v243 offset:56320
	global_load_lds_dwordx4 v[126:127], off
	s_add_i32 m0, s0, 0x2000
	s_add_u32 s0, s6, 0x40080
	v_lshl_add_u64 v[126:127], v[200:201], 0, s[92:93]
	s_addc_u32 s1, s7, 0
	s_add_i32 s4, s5, s69
	global_load_lds_dwordx4 v[126:127], off
	v_lshl_add_u64 v[126:127], s[0:1], 0, v[0:1]
	s_mov_b32 m0, s4
	s_nop 0
	global_load_lds_dwordx4 v[126:127], off
	v_lshl_add_u64 v[126:127], s[0:1], 0, v[214:215]
	s_add_i32 m0, s4, 0x2000
	s_nop 0
	global_load_lds_dwordx4 v[126:127], off
	v_lshl_add_u64 v[126:127], v[206:207], 0, s[92:93]
	s_mov_b32 m0, s84
	s_nop 0
	global_load_lds_dwordx4 v[126:127], off
	v_lshl_add_u64 v[126:127], v[220:221], 0, s[92:93]
	s_mov_b32 m0, s85
	s_nop 0
	global_load_lds_dwordx4 v[126:127], off
	s_waitcnt vmcnt(8)
	s_waitcnt lgkmcnt(0)
	s_barrier
	s_setprio 1
	s_waitcnt lgkmcnt(0)
	v_mfma_i32_16x16x64_i8 v[18:21], v[50:53], v[190:193], v[18:21]
	v_mfma_i32_16x16x64_i8 v[106:109], v[50:53], v[166:169], v[106:109]
	v_mfma_i32_16x16x64_i8 v[46:49], v[114:117], v[166:169], v[46:49]
	v_mfma_i32_16x16x64_i8 v[14:17], v[50:53], v[174:177], v[14:17]
	v_mfma_i32_16x16x64_i8 v[6:9], v[114:117], v[174:177], v[6:9]
	v_mfma_i32_16x16x64_i8 v[90:93], v[50:53], v[182:185], v[90:93]
	v_mfma_i32_16x16x64_i8 v[86:89], v[114:117], v[182:185], v[86:89]
	v_mfma_i32_16x16x64_i8 v[126:129], v[66:69], v[194:197], v[18:21]
	v_mfma_i32_16x16x64_i8 v[18:21], v[114:117], v[190:193], v[22:25]
	v_mfma_i32_16x16x64_i8 v[106:109], v[66:69], v[170:173], v[106:109]
	v_mfma_i32_16x16x64_i8 v[46:49], v[130:133], v[170:173], v[46:49]
	v_mfma_i32_16x16x64_i8 v[14:17], v[66:69], v[178:181], v[14:17]
	v_mfma_i32_16x16x64_i8 v[6:9], v[130:133], v[178:181], v[6:9]
	v_mfma_i32_16x16x64_i8 v[90:93], v[66:69], v[186:189], v[90:93]
	v_mfma_i32_16x16x64_i8 v[86:89], v[130:133], v[186:189], v[86:89]
	v_mfma_i32_16x16x64_i8 v[66:69], v[130:133], v[194:197], v[18:21]
	s_setprio 0
	s_setprio 1
	v_mfma_i32_16x16x64_i8 v[18:21], v[134:137], v[166:169], v[34:37]
	v_mfma_i32_16x16x64_i8 v[114:117], v[154:157], v[170:173], v[18:21]
	v_mfma_i32_16x16x64_i8 v[18:21], v[158:161], v[166:169], v[38:41]
	v_mfma_i32_16x16x64_i8 v[50:53], v[162:165], v[170:173], v[18:21]
	v_mfma_i32_16x16x64_i8 v[18:21], v[134:137], v[182:185], v[82:85]
	v_mfma_i32_16x16x64_i8 v[82:85], v[154:157], v[186:189], v[18:21]
	v_mfma_i32_16x16x64_i8 v[18:21], v[158:161], v[182:185], v[74:77]
	v_mfma_i32_16x16x64_i8 v[74:77], v[162:165], v[186:189], v[18:21]
	v_mfma_i32_16x16x64_i8 v[18:21], v[134:137], v[190:193], v[122:125]
	v_mfma_i32_16x16x64_i8 v[10:13], v[134:137], v[174:177], v[10:13]
	v_mfma_i32_16x16x64_i8 v[2:5], v[158:161], v[174:177], v[2:5]
	v_mfma_i32_16x16x64_i8 v[122:125], v[154:157], v[194:197], v[18:21]
	v_mfma_i32_16x16x64_i8 v[18:21], v[158:161], v[190:193], v[70:73]
	v_mfma_i32_16x16x64_i8 v[10:13], v[154:157], v[178:181], v[10:13]
	v_mfma_i32_16x16x64_i8 v[2:5], v[162:165], v[178:181], v[2:5]
	v_mfma_i32_16x16x64_i8 v[70:73], v[162:165], v[194:197], v[18:21]
	s_setprio 0
	s_barrier
	s_add_i32 vcc_lo, vcc_lo, 2
	s_add_u32 s96, s96, 0x100
	s_addc_u32 s97, s97, 0
	s_cmp_gt_u32 vcc_lo, 13
	s_mov_b64 s[0:1], s[8:9]
	s_cbranch_scc0 .LBB0_80
	s_branch .Lpeelx80

; #define PG8_BAR __builtin_amdgcn_s_barrier()
; template <class Epi, class Sched, bool ALIGN_EPI = false, bool SP2 = false>
; __device__ __forceinline__ void gemm_phase(PG8_LAS unsigned char* lds, const Gemm g, const Sched& S, const Epi& E) {
;     ...
;         if constexpr (ALIGN_EPI) { if (wr == 0) PG8_BAR; }
;         if constexpr (!Epi::AFTER_DRAIN) { E(acc, cur, wr, wc, fr, fq); S.done(cur); }
.Lpeelx80:
	v_readlane_b32 s0, v254, 44
	v_readlane_b32 s1, v254, 45
	s_and_b64 vcc, exec, s[0:1]
	s_cbranch_vccz .LBB0_83
	s_barrier

; #define PG8_STAGE(bufoff, gbase, voff) do { _Pragma("unroll") for (int _i = 0; _i < 2; ++_i) \
;         __builtin_amdgcn_global_load_lds((const unsigned*)((const char*)(gbase) + (voff)[_i]), (PG8_LAS unsigned*)(lds + (bufoff) + ldsw + _i * 8192), 16, 0, 0); } while (0)
; #define PG8_LDA(dst, b, h) do { _Pragma("unroll") for (int m = 0; m < 4; ++m) _Pragma("unroll") for (int k = 0; k < 2; ++k) dst[m][k] = *(const PG8_LAS bf16x8*)(lds + PG8_SA(b, h) + aoff + m * 2048 + k * 1024); } while (0)
; #define PG8_LDB(dst, b, h) do { _Pragma("unroll") for (int n = 0; n < 2; ++n) _Pragma("unroll") for (int k = 0; k < 2; ++k) dst[n][k] = *(const PG8_LAS bf16x8*)(lds + PG8_SB(b, h) + boff + n * 2048 + k * 1024); } while (0)
; #define PG8_MMA(ai, bj, At, Bt) do { __builtin_amdgcn_s_setprio(1); _Pragma("unroll") for (int m = 0; m < 4; ++m) _Pragma("unroll") for (int n = 0; n < 2; ++n) _Pragma("unroll") for (int k = 0; k < 2; ++k) \
;         acc[ai][bj][m][n] = mma16<Epi::I8>(Bt[n][k], At[m][k], acc[ai][bj][m][n]); __builtin_amdgcn_s_setprio(0); } while (0)
; #define PG8_WAIT_V(n) asm volatile("s_waitcnt vmcnt(" #n ")" ::: "memory")
; #define PG8_WAIT_L(n) asm volatile("s_waitcnt lgkmcnt(" #n ")" ::: "memory")
; #define PG8_BAR __builtin_amdgcn_s_barrier()
; #define PG8_SCHED __builtin_amdgcn_sched_barrier(0)
; template <class Epi, class Sched, bool ALIGN_EPI = false, bool SP2 = false>
; __device__ __forceinline__ void gemm_phase(PG8_LAS unsigned char* lds, const Gemm g, const Sched& S, const Epi& E) {
;     ...
;             PG8_LDB(B0, 0, 0); PG8_LDB(B1, 0, 1); PG8_SCHED; PG8_LDA(At, 0, 0); PG8_STAGE(PG8_SA(1, 1), a1 + hstep, voffA);
;             PG8_WAIT_V(8); PG8_WAIT_L(0); PG8_BAR; PG8_MMA(0, 0, At, B0); PG8_MMA(0, 1, At, B1); PG8_BAR; PG8_SCHED;
;             PG8_LDA(At, 0, 1); PG8_STAGE(PG8_SB(0, 0), b2, voffB); PG8_STAGE(PG8_SB(0, 1), b2 + hstep, voffB); PG8_STAGE(PG8_SA(0, 0), a2, voffA);
;             PG8_WAIT_V(8); PG8_WAIT_L(0); PG8_BAR; PG8_MMA(1, 0, At, B0); PG8_MMA(1, 1, At, B1); PG8_BAR; PG8_SCHED;
;     ...
;         for (int a = 0; a < 2; ++a)
; #pragma unroll
;             for (int b = 0; b < 2; ++b)
; #pragma unroll
;                 for (int m = 0; m < 4; ++m)
; #pragma unroll
;                     for (int n = 0; n < 2; ++n) acc[a][b][m][n] = (f32x4){0.f, 0.f, 0.f, 0.f};
;         cur = nxt; cA = nA; cB = nB; ++ui;
.LBB0_174:
	s_add_u32 s6, s6, 0x80
	s_addc_u32 s7, s7, 0
	s_add_u32 s67, s8, 0x100
	s_addc_u32 s85, s9, 0
	s_mov_b32 s8, 0
	s_waitcnt vmcnt(0)
.Lpeel175:
	s_add_i32 vcc_lo, s8, 2
	s_add_u32 s4, s6, 0x80
	s_addc_u32 s5, s7, 0
	s_add_i32 vcc_hi, 0, 0x10000
	s_cmp_eq_u32 s13, s8
	s_cselect_b32 s9, s1, s5
	s_cselect_b32 s8, s0, s4
	s_cselect_b32 s5, s97, s85
	s_cselect_b32 s4, s96, s67
	s_add_i32 s84, 0, 0x14000
	v_add_u32_e32 v122, vcc_hi, v248
	v_add_u32_e32 v154, s84, v248
	ds_read_b128 v[98:101], v122
	ds_read_b128 v[102:105], v122 offset:1024
	ds_read_b128 v[114:117], v122 offset:2048
	ds_read_b128 v[122:125], v122 offset:3072
	ds_read_b128 v[130:133], v154
	ds_read_b128 v[138:141], v154 offset:1024
	ds_read_b128 v[146:149], v154 offset:2048
	ds_read_b128 v[154:157], v154 offset:3072
	v_lshl_add_u64 v[206:207], s[6:7], 0, v[200:201]
	s_add_i32 m0, s81, 0xc000
	ds_read_b128 v[162:165], v249
	ds_read_b128 v[166:169], v249 offset:1024
	ds_read_b128 v[170:173], v249 offset:2048
	ds_read_b128 v[174:177], v249 offset:3072
	ds_read_b128 v[178:181], v249 offset:4096
	ds_read_b128 v[182:185], v249 offset:5120
	ds_read_b128 v[186:189], v249 offset:6144
	ds_read_b128 v[190:193], v249 offset:7168
	global_load_lds_dwordx4 v[206:207], off
	v_lshl_add_u64 v[206:207], s[6:7], 0, v[210:211]
	s_add_i32 m0, s81, 0xe000
	s_nop 0
	global_load_lds_dwordx4 v[206:207], off
	s_waitcnt vmcnt(8)
	s_waitcnt lgkmcnt(0)
	s_barrier
	s_setprio 1
	s_waitcnt lgkmcnt(0)
	v_mfma_f32_16x16x32_bf16 v[158:161], v[98:101], v[162:165], 0
	v_mfma_f32_16x16x32_bf16 v[150:153], v[114:117], v[162:165], 0
	v_mfma_f32_16x16x32_bf16 v[126:129], v[98:101], v[170:173], 0
	v_mfma_f32_16x16x32_bf16 v[118:121], v[114:117], v[170:173], 0
	v_mfma_f32_16x16x32_bf16 v[94:97], v[98:101], v[178:181], 0
	v_mfma_f32_16x16x32_bf16 v[90:93], v[114:117], v[178:181], 0
	v_mfma_f32_16x16x32_bf16 v[78:81], v[98:101], v[186:189], 0
	v_mfma_f32_16x16x32_bf16 v[74:77], v[114:117], v[186:189], 0
	v_mfma_f32_16x16x32_bf16 v[158:161], v[102:105], v[166:169], v[158:161]
	v_mfma_f32_16x16x32_bf16 v[150:153], v[122:125], v[166:169], v[150:153]
	v_mfma_f32_16x16x32_bf16 v[126:129], v[102:105], v[174:177], v[126:129]
	v_mfma_f32_16x16x32_bf16 v[118:121], v[122:125], v[174:177], v[118:121]
	v_mfma_f32_16x16x32_bf16 v[94:97], v[102:105], v[182:185], v[94:97]
	v_mfma_f32_16x16x32_bf16 v[90:93], v[122:125], v[182:185], v[90:93]
	v_mfma_f32_16x16x32_bf16 v[78:81], v[102:105], v[190:193], v[78:81]
	v_mfma_f32_16x16x32_bf16 v[74:77], v[122:125], v[190:193], v[74:77]
	s_setprio 0
	s_setprio 1
	v_mfma_f32_16x16x32_bf16 v[142:145], v[130:133], v[162:165], 0
	v_mfma_f32_16x16x32_bf16 v[134:137], v[146:149], v[162:165], 0
	v_mfma_f32_16x16x32_bf16 v[110:113], v[130:133], v[170:173], 0
	v_mfma_f32_16x16x32_bf16 v[106:109], v[146:149], v[170:173], 0
	v_mfma_f32_16x16x32_bf16 v[86:89], v[130:133], v[178:181], 0
	v_mfma_f32_16x16x32_bf16 v[82:85], v[146:149], v[178:181], 0
	v_mfma_f32_16x16x32_bf16 v[70:73], v[130:133], v[186:189], 0
	v_mfma_f32_16x16x32_bf16 v[66:69], v[146:149], v[186:189], 0
	v_mfma_f32_16x16x32_bf16 v[142:145], v[138:141], v[166:169], v[142:145]
	v_mfma_f32_16x16x32_bf16 v[134:137], v[154:157], v[166:169], v[134:137]
	v_mfma_f32_16x16x32_bf16 v[110:113], v[138:141], v[174:177], v[110:113]
	v_mfma_f32_16x16x32_bf16 v[106:109], v[154:157], v[174:177], v[106:109]
	v_mfma_f32_16x16x32_bf16 v[86:89], v[138:141], v[182:185], v[86:89]
	v_mfma_f32_16x16x32_bf16 v[82:85], v[154:157], v[182:185], v[82:85]
	v_mfma_f32_16x16x32_bf16 v[70:73], v[138:141], v[190:193], v[70:73]
	v_mfma_f32_16x16x32_bf16 v[66:69], v[154:157], v[190:193], v[66:69]
	s_setprio 0
	s_barrier
	s_add_i32 vcc_hi, vcc_hi, s80
	v_lshl_add_u64 v[206:207], s[4:5], 0, v[0:1]
	s_mov_b32 m0, vcc_hi
	ds_read_b128 v[162:165], v249 offset:16384
	ds_read_b128 v[166:169], v249 offset:17408
	ds_read_b128 v[170:173], v249 offset:18432
	ds_read_b128 v[174:177], v249 offset:19456
	ds_read_b128 v[178:181], v249 offset:20480
	ds_read_b128 v[182:185], v249 offset:21504
	ds_read_b128 v[186:189], v249 offset:22528
	ds_read_b128 v[190:193], v249 offset:23552
	global_load_lds_dwordx4 v[206:207], off
	s_add_i32 m0, vcc_hi, 0x2000
	v_lshl_add_u64 v[212:213], s[4:5], 0, v[198:199]
	s_add_u32 s4, s4, s58
	s_addc_u32 s5, s5, 0
	s_add_i32 s84, s84, s80
	global_load_lds_dwordx4 v[212:213], off
	v_lshl_add_u64 v[214:215], s[4:5], 0, v[0:1]
	s_mov_b32 m0, s84
	v_lshl_add_u64 v[216:217], s[4:5], 0, v[198:199]
	global_load_lds_dwordx4 v[214:215], off
	s_add_i32 m0, s84, 0x2000
	v_lshl_add_u64 v[218:219], s[8:9], 0, v[194:195]
	global_load_lds_dwordx4 v[216:217], off
	s_mov_b32 m0, s81
	v_lshl_add_u64 v[220:221], s[8:9], 0, v[196:197]
	global_load_lds_dwordx4 v[218:219], off
	s_mov_b32 m0, s70
	s_nop 0
	global_load_lds_dwordx4 v[220:221], off
	s_waitcnt vmcnt(8)
	s_waitcnt lgkmcnt(0)
	s_barrier
; #define PG8_STAGE(bufoff, gbase, voff) do { _Pragma("unroll") for (int _i = 0; _i < 2; ++_i) \
;         __builtin_amdgcn_global_load_lds((const unsigned*)((const char*)(gbase) + (voff)[_i]), (PG8_LAS unsigned*)(lds + (bufoff) + ldsw + _i * 8192), 16, 0, 0); } while (0)
; #define PG8_LDA(dst, b, h) do { _Pragma("unroll") for (int m = 0; m < 4; ++m) _Pragma("unroll") for (int k = 0; k < 2; ++k) dst[m][k] = *(const PG8_LAS bf16x8*)(lds + PG8_SA(b, h) + aoff + m * 2048 + k * 1024); } while (0)
; #define PG8_LDB(dst, b, h) do { _Pragma("unroll") for (int n = 0; n < 2; ++n) _Pragma("unroll") for (int k = 0; k < 2; ++k) dst[n][k] = *(const PG8_LAS bf16x8*)(lds + PG8_SB(b, h) + boff + n * 2048 + k * 1024); } while (0)
; #define PG8_MMA(ai, bj, At, Bt) do { __builtin_amdgcn_s_setprio(1); _Pragma("unroll") for (int m = 0; m < 4; ++m) _Pragma("unroll") for (int n = 0; n < 2; ++n) _Pragma("unroll") for (int k = 0; k < 2; ++k) \
;         acc[ai][bj][m][n] = mma16<Epi::I8>(Bt[n][k], At[m][k], acc[ai][bj][m][n]); __builtin_amdgcn_s_setprio(0); } while (0)
; #define PG8_WAIT_V(n) asm volatile("s_waitcnt vmcnt(" #n ")" ::: "memory")
; #define PG8_WAIT_L(n) asm volatile("s_waitcnt lgkmcnt(" #n ")" ::: "memory")
; #define PG8_BAR __builtin_amdgcn_s_barrier()
; #define PG8_SCHED __builtin_amdgcn_sched_barrier(0)
; template <class Epi, class Sched, bool ALIGN_EPI = false, bool SP2 = false>
; __device__ __forceinline__ void gemm_phase(PG8_LAS unsigned char* lds, const Gemm g, const Sched& S, const Epi& E) {
;     ...
;             PG8_WAIT_V(8); PG8_WAIT_L(0); PG8_BAR; PG8_MMA(1, 0, At, B0); PG8_MMA(1, 1, At, B1); PG8_BAR; PG8_SCHED;
;             PG8_LDB(B0, 1, 0); PG8_LDB(B1, 1, 1); PG8_SCHED; PG8_LDA(At, 1, 0); PG8_STAGE(PG8_SA(0, 1), a2 + hstep, voffA);
;             PG8_WAIT_V(8); PG8_WAIT_L(0); PG8_BAR; PG8_MMA(0, 0, At, B0); PG8_MMA(0, 1, At, B1); PG8_BAR; PG8_SCHED;
	s_setprio 1
	s_waitcnt lgkmcnt(0)
	v_mfma_f32_16x16x32_bf16 v[62:65], v[98:101], v[162:165], 0
	v_mfma_f32_16x16x32_bf16 v[58:61], v[114:117], v[162:165], 0
	v_mfma_f32_16x16x32_bf16 v[46:49], v[98:101], v[170:173], 0
	v_mfma_f32_16x16x32_bf16 v[42:45], v[114:117], v[170:173], 0
	v_mfma_f32_16x16x32_bf16 v[30:33], v[98:101], v[178:181], 0
	v_mfma_f32_16x16x32_bf16 v[26:29], v[114:117], v[178:181], 0
	v_mfma_f32_16x16x32_bf16 v[14:17], v[98:101], v[186:189], 0
	v_mfma_f32_16x16x32_bf16 v[10:13], v[114:117], v[186:189], 0
	v_mfma_f32_16x16x32_bf16 v[62:65], v[102:105], v[166:169], v[62:65]
	v_mfma_f32_16x16x32_bf16 v[58:61], v[122:125], v[166:169], v[58:61]
	v_mfma_f32_16x16x32_bf16 v[46:49], v[102:105], v[174:177], v[46:49]
	v_mfma_f32_16x16x32_bf16 v[42:45], v[122:125], v[174:177], v[42:45]
	v_mfma_f32_16x16x32_bf16 v[30:33], v[102:105], v[182:185], v[30:33]
	v_mfma_f32_16x16x32_bf16 v[26:29], v[122:125], v[182:185], v[26:29]
	v_mfma_f32_16x16x32_bf16 v[14:17], v[102:105], v[190:193], v[14:17]
	v_mfma_f32_16x16x32_bf16 v[10:13], v[122:125], v[190:193], v[10:13]
	s_setprio 0
	s_setprio 1
	v_mfma_f32_16x16x32_bf16 v[54:57], v[130:133], v[162:165], 0
	v_mfma_f32_16x16x32_bf16 v[50:53], v[146:149], v[162:165], 0
	v_mfma_f32_16x16x32_bf16 v[38:41], v[130:133], v[170:173], 0
	v_mfma_f32_16x16x32_bf16 v[34:37], v[146:149], v[170:173], 0
	v_mfma_f32_16x16x32_bf16 v[22:25], v[130:133], v[178:181], 0
	v_mfma_f32_16x16x32_bf16 v[18:21], v[146:149], v[178:181], 0
	v_mfma_f32_16x16x32_bf16 v[6:9], v[130:133], v[186:189], 0
	v_mfma_f32_16x16x32_bf16 v[2:5], v[146:149], v[186:189], 0
	v_mfma_f32_16x16x32_bf16 v[54:57], v[138:141], v[166:169], v[54:57]
	v_mfma_f32_16x16x32_bf16 v[50:53], v[154:157], v[166:169], v[50:53]
	v_mfma_f32_16x16x32_bf16 v[38:41], v[138:141], v[174:177], v[38:41]
	v_mfma_f32_16x16x32_bf16 v[34:37], v[154:157], v[174:177], v[34:37]
	v_mfma_f32_16x16x32_bf16 v[22:25], v[138:141], v[182:185], v[22:25]
	v_mfma_f32_16x16x32_bf16 v[18:21], v[154:157], v[182:185], v[18:21]
	v_mfma_f32_16x16x32_bf16 v[6:9], v[138:141], v[190:193], v[6:9]
	v_mfma_f32_16x16x32_bf16 v[2:5], v[154:157], v[190:193], v[2:5]
	s_setprio 0
	s_barrier
	s_add_i32 s84, 0, 0x18000
	s_add_i32 vcc_hi, 0, 0x1c000
	v_add_u32_e32 v122, s84, v248
	v_add_u32_e32 v154, vcc_hi, v248
	ds_read_b128 v[98:101], v122
	ds_read_b128 v[102:105], v122 offset:1024
	ds_read_b128 v[114:117], v122 offset:2048
	ds_read_b128 v[122:125], v122 offset:3072
	ds_read_b128 v[130:133], v154
	ds_read_b128 v[138:141], v154 offset:1024
	ds_read_b128 v[146:149], v154 offset:2048
	ds_read_b128 v[154:157], v154 offset:3072
	s_add_u32 s4, s8, s58
	s_addc_u32 s5, s9, 0
	s_mov_b32 m0, s71
	v_lshl_add_u64 v[222:223], s[4:5], 0, v[194:195]
	ds_read_b128 v[162:165], v249 offset:32768
	ds_read_b128 v[166:169], v249 offset:33792
	ds_read_b128 v[170:173], v249 offset:34816
	ds_read_b128 v[174:177], v249 offset:35840
	ds_read_b128 v[178:181], v249 offset:36864
	ds_read_b128 v[182:185], v249 offset:37888
	ds_read_b128 v[186:189], v249 offset:38912
	ds_read_b128 v[190:193], v249 offset:39936
	global_load_lds_dwordx4 v[222:223], off
	v_lshl_add_u64 v[222:223], s[4:5], 0, v[196:197]
	s_mov_b32 m0, s12
	s_nop 0
	global_load_lds_dwordx4 v[222:223], off
	s_waitcnt vmcnt(8)
	s_waitcnt lgkmcnt(0)
	s_barrier
	s_setprio 1
	s_waitcnt lgkmcnt(0)
	v_mfma_f32_16x16x32_bf16 v[158:161], v[98:101], v[162:165], v[158:161]
	v_mfma_f32_16x16x32_bf16 v[150:153], v[114:117], v[162:165], v[150:153]
	v_mfma_f32_16x16x32_bf16 v[126:129], v[98:101], v[170:173], v[126:129]
	v_mfma_f32_16x16x32_bf16 v[118:121], v[114:117], v[170:173], v[118:121]
	v_mfma_f32_16x16x32_bf16 v[94:97], v[98:101], v[178:181], v[94:97]
	v_mfma_f32_16x16x32_bf16 v[90:93], v[114:117], v[178:181], v[90:93]
	v_mfma_f32_16x16x32_bf16 v[78:81], v[98:101], v[186:189], v[78:81]
	v_mfma_f32_16x16x32_bf16 v[74:77], v[114:117], v[186:189], v[74:77]
	v_mfma_f32_16x16x32_bf16 v[158:161], v[102:105], v[166:169], v[158:161]
	v_mfma_f32_16x16x32_bf16 v[150:153], v[122:125], v[166:169], v[150:153]
	v_mfma_f32_16x16x32_bf16 v[126:129], v[102:105], v[174:177], v[126:129]
	v_mfma_f32_16x16x32_bf16 v[118:121], v[122:125], v[174:177], v[118:121]
	v_mfma_f32_16x16x32_bf16 v[94:97], v[102:105], v[182:185], v[94:97]
	v_mfma_f32_16x16x32_bf16 v[90:93], v[122:125], v[182:185], v[90:93]
	v_mfma_f32_16x16x32_bf16 v[78:81], v[102:105], v[190:193], v[78:81]
	v_mfma_f32_16x16x32_bf16 v[74:77], v[122:125], v[190:193], v[74:77]
	s_setprio 0
	s_setprio 1
	v_mfma_f32_16x16x32_bf16 v[142:145], v[130:133], v[162:165], v[142:145]
	v_mfma_f32_16x16x32_bf16 v[134:137], v[146:149], v[162:165], v[134:137]
	v_mfma_f32_16x16x32_bf16 v[110:113], v[130:133], v[170:173], v[110:113]
	v_mfma_f32_16x16x32_bf16 v[106:109], v[146:149], v[170:173], v[106:109]
	v_mfma_f32_16x16x32_bf16 v[86:89], v[130:133], v[178:181], v[86:89]
	v_mfma_f32_16x16x32_bf16 v[82:85], v[146:149], v[178:181], v[82:85]
	v_mfma_f32_16x16x32_bf16 v[70:73], v[130:133], v[186:189], v[70:73]
	v_mfma_f32_16x16x32_bf16 v[66:69], v[146:149], v[186:189], v[66:69]
	v_mfma_f32_16x16x32_bf16 v[142:145], v[138:141], v[166:169], v[142:145]
	v_mfma_f32_16x16x32_bf16 v[134:137], v[154:157], v[166:169], v[134:137]
	v_mfma_f32_16x16x32_bf16 v[110:113], v[138:141], v[174:177], v[110:113]
	v_mfma_f32_16x16x32_bf16 v[106:109], v[154:157], v[174:177], v[106:109]
	v_mfma_f32_16x16x32_bf16 v[86:89], v[138:141], v[182:185], v[86:89]
	v_mfma_f32_16x16x32_bf16 v[82:85], v[154:157], v[182:185], v[82:85]
	v_mfma_f32_16x16x32_bf16 v[70:73], v[138:141], v[190:193], v[70:73]
	v_mfma_f32_16x16x32_bf16 v[66:69], v[154:157], v[190:193], v[66:69]
	s_setprio 0
	s_barrier
; #define PG8_STAGE(bufoff, gbase, voff) do { _Pragma("unroll") for (int _i = 0; _i < 2; ++_i) \
;         __builtin_amdgcn_global_load_lds((const unsigned*)((const char*)(gbase) + (voff)[_i]), (PG8_LAS unsigned*)(lds + (bufoff) + ldsw + _i * 8192), 16, 0, 0); } while (0)
; #define PG8_LDA(dst, b, h) do { _Pragma("unroll") for (int m = 0; m < 4; ++m) _Pragma("unroll") for (int k = 0; k < 2; ++k) dst[m][k] = *(const PG8_LAS bf16x8*)(lds + PG8_SA(b, h) + aoff + m * 2048 + k * 1024); } while (0)
; #define PG8_MMA(ai, bj, At, Bt) do { __builtin_amdgcn_s_setprio(1); _Pragma("unroll") for (int m = 0; m < 4; ++m) _Pragma("unroll") for (int n = 0; n < 2; ++n) _Pragma("unroll") for (int k = 0; k < 2; ++k) \
;         acc[ai][bj][m][n] = mma16<Epi::I8>(Bt[n][k], At[m][k], acc[ai][bj][m][n]); __builtin_amdgcn_s_setprio(0); } while (0)
; #define PG8_WAIT_V(n) asm volatile("s_waitcnt vmcnt(" #n ")" ::: "memory")
; #define PG8_WAIT_L(n) asm volatile("s_waitcnt lgkmcnt(" #n ")" ::: "memory")
; #define PG8_BAR __builtin_amdgcn_s_barrier()
; #define PG8_SCHED __builtin_amdgcn_sched_barrier(0)
; template <class Epi, class Sched, bool ALIGN_EPI = false, bool SP2 = false>
; __device__ __forceinline__ void gemm_phase(PG8_LAS unsigned char* lds, const Gemm g, const Sched& S, const Epi& E) {
;     ...
;         for (int t = 0; t < nt; t += 2) {
;     ...
;             PG8_LDA(At, 1, 1); PG8_STAGE(PG8_SB(1, 0), b3, voffB); PG8_STAGE(PG8_SB(1, 1), b3 + hstep, voffB); PG8_STAGE(PG8_SA(1, 0), a3, voffA);
;             PG8_WAIT_V(8); PG8_WAIT_L(0); PG8_BAR; PG8_MMA(1, 0, At, B0); PG8_MMA(1, 1, At, B1); PG8_BAR; PG8_SCHED;
	s_add_i32 s4, s84, s80
	v_lshl_add_u64 v[206:207], v[206:207], 0, s[92:93]
	s_mov_b32 m0, s4
	ds_read_b128 v[162:165], v249 offset:49152
	ds_read_b128 v[166:169], v249 offset:50176
	ds_read_b128 v[170:173], v249 offset:51200
	ds_read_b128 v[174:177], v249 offset:52224
	ds_read_b128 v[178:181], v249 offset:53248
	ds_read_b128 v[182:185], v249 offset:54272
	ds_read_b128 v[186:189], v249 offset:55296
	ds_read_b128 v[190:193], v249 offset:56320
	global_load_lds_dwordx4 v[206:207], off
	v_lshl_add_u64 v[206:207], v[212:213], 0, s[92:93]
	s_add_i32 m0, s4, 0x2000
	s_add_i32 s4, vcc_hi, s80
	global_load_lds_dwordx4 v[206:207], off
	v_lshl_add_u64 v[206:207], v[214:215], 0, s[92:93]
	s_mov_b32 m0, s4
	s_nop 0
	global_load_lds_dwordx4 v[206:207], off
	v_lshl_add_u64 v[206:207], v[216:217], 0, s[92:93]
	s_add_i32 m0, s4, 0x2000
	s_nop 0
	global_load_lds_dwordx4 v[206:207], off
	v_lshl_add_u64 v[206:207], v[218:219], 0, s[92:93]
	s_mov_b32 m0, s10
	s_nop 0
	global_load_lds_dwordx4 v[206:207], off
	v_lshl_add_u64 v[206:207], v[220:221], 0, s[92:93]
	s_mov_b32 m0, s11
	s_nop 0
	global_load_lds_dwordx4 v[206:207], off
	s_waitcnt vmcnt(8)
	s_waitcnt lgkmcnt(0)
	s_barrier
	s_setprio 1
	s_waitcnt lgkmcnt(0)
	v_mfma_f32_16x16x32_bf16 v[62:65], v[98:101], v[162:165], v[62:65]
	v_mfma_f32_16x16x32_bf16 v[58:61], v[114:117], v[162:165], v[58:61]
	v_mfma_f32_16x16x32_bf16 v[46:49], v[98:101], v[170:173], v[46:49]
	v_mfma_f32_16x16x32_bf16 v[42:45], v[114:117], v[170:173], v[42:45]
	v_mfma_f32_16x16x32_bf16 v[30:33], v[98:101], v[178:181], v[30:33]
	v_mfma_f32_16x16x32_bf16 v[26:29], v[114:117], v[178:181], v[26:29]
	v_mfma_f32_16x16x32_bf16 v[14:17], v[98:101], v[186:189], v[14:17]
	v_mfma_f32_16x16x32_bf16 v[10:13], v[114:117], v[186:189], v[10:13]
	v_mfma_f32_16x16x32_bf16 v[62:65], v[102:105], v[166:169], v[62:65]
	v_mfma_f32_16x16x32_bf16 v[58:61], v[122:125], v[166:169], v[58:61]
	v_mfma_f32_16x16x32_bf16 v[46:49], v[102:105], v[174:177], v[46:49]
	v_mfma_f32_16x16x32_bf16 v[42:45], v[122:125], v[174:177], v[42:45]
	v_mfma_f32_16x16x32_bf16 v[30:33], v[102:105], v[182:185], v[30:33]
	v_mfma_f32_16x16x32_bf16 v[26:29], v[122:125], v[182:185], v[26:29]
	v_mfma_f32_16x16x32_bf16 v[14:17], v[102:105], v[190:193], v[14:17]
	v_mfma_f32_16x16x32_bf16 v[10:13], v[122:125], v[190:193], v[10:13]
	s_setprio 0
	s_setprio 1
	v_mfma_f32_16x16x32_bf16 v[54:57], v[130:133], v[162:165], v[54:57]
	v_mfma_f32_16x16x32_bf16 v[50:53], v[146:149], v[162:165], v[50:53]
	v_mfma_f32_16x16x32_bf16 v[38:41], v[130:133], v[170:173], v[38:41]
	v_mfma_f32_16x16x32_bf16 v[34:37], v[146:149], v[170:173], v[34:37]
	v_mfma_f32_16x16x32_bf16 v[22:25], v[130:133], v[178:181], v[22:25]
	v_mfma_f32_16x16x32_bf16 v[18:21], v[146:149], v[178:181], v[18:21]
	v_mfma_f32_16x16x32_bf16 v[6:9], v[130:133], v[186:189], v[6:9]
	v_mfma_f32_16x16x32_bf16 v[2:5], v[146:149], v[186:189], v[2:5]
	v_mfma_f32_16x16x32_bf16 v[54:57], v[138:141], v[166:169], v[54:57]
	v_mfma_f32_16x16x32_bf16 v[50:53], v[154:157], v[166:169], v[50:53]
	v_mfma_f32_16x16x32_bf16 v[38:41], v[138:141], v[174:177], v[38:41]
	v_mfma_f32_16x16x32_bf16 v[34:37], v[154:157], v[174:177], v[34:37]
	v_mfma_f32_16x16x32_bf16 v[22:25], v[138:141], v[182:185], v[22:25]
	v_mfma_f32_16x16x32_bf16 v[18:21], v[154:157], v[182:185], v[18:21]
	v_mfma_f32_16x16x32_bf16 v[6:9], v[138:141], v[190:193], v[6:9]
	v_mfma_f32_16x16x32_bf16 v[2:5], v[154:157], v[190:193], v[2:5]
	s_setprio 0
	s_barrier
	s_add_u32 s6, s6, 0x100
	s_addc_u32 s7, s7, 0
	s_add_u32 s67, s67, 0x100
	s_addc_u32 s85, s85, 0
	s_cmp_ge_u32 vcc_lo, s69
	s_mov_b32 s8, vcc_lo
	s_cbranch_scc0 .LBB0_175
	s_branch .Lpeelx175

; #define PG8_BAR __builtin_amdgcn_s_barrier()
; template <class Epi, class Sched, bool ALIGN_EPI = false, bool SP2 = false>
; __device__ __forceinline__ void gemm_phase(PG8_LAS unsigned char* lds, const Gemm g, const Sched& S, const Epi& E) {
;     ...
;         if constexpr (ALIGN_EPI) { if (wr == 0) PG8_BAR; }
;         if constexpr (!Epi::AFTER_DRAIN) { E(acc, cur, wr, wc, fr, fq); S.done(cur); }
.Lpeelx175:
	v_mov_b32_e32 v232, 0x8800
	v_mov_b32_e32 v231, 0x2000
	v_mov_b32_e32 v202, 1
	s_and_b64 vcc, exec, s[46:47]
	s_cbranch_vccz .LBB0_178
	s_barrier

; #define PG8_STAGE(bufoff, gbase, voff) do { _Pragma("unroll") for (int _i = 0; _i < 2; ++_i) \
;         __builtin_amdgcn_global_load_lds((const unsigned*)((const char*)(gbase) + (voff)[_i]), (PG8_LAS unsigned*)(lds + (bufoff) + ldsw + _i * 8192), 16, 0, 0); } while (0)
; #define PG8_LDA(dst, b, h) do { _Pragma("unroll") for (int m = 0; m < 4; ++m) _Pragma("unroll") for (int k = 0; k < 2; ++k) dst[m][k] = *(const PG8_LAS bf16x8*)(lds + PG8_SA(b, h) + aoff + m * 2048 + k * 1024); } while (0)
; #define PG8_LDB(dst, b, h) do { _Pragma("unroll") for (int n = 0; n < 2; ++n) _Pragma("unroll") for (int k = 0; k < 2; ++k) dst[n][k] = *(const PG8_LAS bf16x8*)(lds + PG8_SB(b, h) + boff + n * 2048 + k * 1024); } while (0)
; #define PG8_MMA(ai, bj, At, Bt) do { __builtin_amdgcn_s_setprio(1); _Pragma("unroll") for (int m = 0; m < 4; ++m) _Pragma("unroll") for (int n = 0; n < 2; ++n) _Pragma("unroll") for (int k = 0; k < 2; ++k) \
;         acc[ai][bj][m][n] = mma16<Epi::I8>(Bt[n][k], At[m][k], acc[ai][bj][m][n]); __builtin_amdgcn_s_setprio(0); } while (0)
; #define PG8_WAIT_V(n) asm volatile("s_waitcnt vmcnt(" #n ")" ::: "memory")
; #define PG8_WAIT_L(n) asm volatile("s_waitcnt lgkmcnt(" #n ")" ::: "memory")
; #define PG8_BAR __builtin_amdgcn_s_barrier()
; #define PG8_SCHED __builtin_amdgcn_sched_barrier(0)
; template <class Epi, class Sched, bool ALIGN_EPI = false, bool SP2 = false>
; __device__ __forceinline__ void gemm_phase(PG8_LAS unsigned char* lds, const Gemm g, const Sched& S, const Epi& E) {
;     ...
;             PG8_LDB(B0, 0, 0); PG8_LDB(B1, 0, 1); PG8_SCHED; PG8_LDA(At, 0, 0); PG8_STAGE(PG8_SA(1, 1), a1 + hstep, voffA);
;             PG8_WAIT_V(8); PG8_WAIT_L(0); PG8_BAR; PG8_MMA(0, 0, At, B0); PG8_MMA(0, 1, At, B1); PG8_BAR; PG8_SCHED;
;             PG8_LDA(At, 0, 1); PG8_STAGE(PG8_SB(0, 0), b2, voffB); PG8_STAGE(PG8_SB(0, 1), b2 + hstep, voffB); PG8_STAGE(PG8_SA(0, 0), a2, voffA);
;             PG8_WAIT_V(8); PG8_WAIT_L(0); PG8_BAR; PG8_MMA(1, 0, At, B0); PG8_MMA(1, 1, At, B1); PG8_BAR; PG8_SCHED;
;     ...
;         for (int a = 0; a < 2; ++a)
; #pragma unroll
;             for (int b = 0; b < 2; ++b)
; #pragma unroll
;                 for (int m = 0; m < 4; ++m)
; #pragma unroll
;                     for (int n = 0; n < 2; ++n) acc[a][b][m][n] = (f32x4){0.f, 0.f, 0.f, 0.f};
;         cur = nxt; cA = nA; cB = nB; ++ui;
.LBB0_290:
	s_ashr_i32 s11, s10, 31
	s_mov_b32 s40, s10
	s_lshl_b64 s[10:11], s[10:11], 19
	v_readlane_b32 s16, v252, 41
	v_readlane_b32 s17, v252, 42
	s_add_u32 s16, s16, s10
	s_addc_u32 s17, s17, s11
	s_and_b64 s[10:11], s[96:97], exec
	s_cselect_b32 s5, s17, s9
	s_cselect_b32 s7, s16, s8
	s_ashr_i32 s51, s50, 31
	s_lshl_b64 s[10:11], s[50:51], 19
	s_add_u32 s82, s41, s10
	s_addc_u32 s83, s29, s11
	s_and_b64 s[10:11], s[96:97], exec
	s_cselect_b32 s11, s83, s85
	s_cselect_b32 s67, s82, s84
	s_add_u32 s69, s84, 0x100
	s_mov_b64 s[38:39], s[16:17]
	s_mov_b64 s[20:21], s[96:97]
	s_addc_u32 s68, s85, 0
	s_mov_b32 s10, -2
.Lpeel291:
	s_add_u32 s84, s8, 0x100
	s_addc_u32 s85, s9, 0
	s_add_i32 s66, 0, 0x10000
	s_cmp_eq_u32 s10, 12
	s_cselect_b32 vcc_hi, s5, s85
	s_cselect_b32 vcc_lo, s7, s84
	s_cselect_b32 s97, s11, s68
	s_cselect_b32 s96, s67, s69
	s_add_i32 s70, 0, 0x14000
	v_add_u32_e32 v110, s66, v175
	v_add_u32_e32 v168, s70, v175
	s_waitcnt vmcnt(0)
	ds_read_b128 v[66:69], v110
	ds_read_b128 v[70:73], v110 offset:1024
	ds_read_b128 v[106:109], v110 offset:2048
	ds_read_b128 v[110:113], v110 offset:3072
	ds_read_b128 v[114:117], v168
	ds_read_b128 v[118:121], v168 offset:1024
	ds_read_b128 v[126:129], v168 offset:2048
	ds_read_b128 v[178:181], v168 offset:3072
	v_lshl_add_u64 v[168:169], s[8:9], 0, v[164:165]
	s_add_i32 m0, s1, 0xc000
	ds_read_b128 v[182:185], v177
	ds_read_b128 v[186:189], v177 offset:1024
	ds_read_b128 v[190:193], v177 offset:2048
	ds_read_b128 v[194:197], v177 offset:3072
	ds_read_b128 v[198:201], v177 offset:4096
	ds_read_b128 v[210:213], v177 offset:5120
	ds_read_b128 v[214:217], v177 offset:6144
	ds_read_b128 v[218:221], v177 offset:7168
	global_load_lds_dwordx4 v[168:169], off
	v_lshl_add_u64 v[168:169], s[8:9], 0, v[166:167]
	s_add_i32 m0, s1, 0xe000
	s_nop 0
	global_load_lds_dwordx4 v[168:169], off
	s_waitcnt vmcnt(8)
	s_waitcnt lgkmcnt(0)
	s_barrier
	s_setprio 1
	s_waitcnt lgkmcnt(0)
	v_mfma_i32_16x16x64_i8 v[154:157], v[66:69], v[182:185], 0
	v_mfma_i32_16x16x64_i8 v[146:149], v[106:109], v[182:185], 0
	v_mfma_i32_16x16x64_i8 v[150:153], v[66:69], v[190:193], 0
	v_mfma_i32_16x16x64_i8 v[138:141], v[106:109], v[190:193], 0
	v_mfma_i32_16x16x64_i8 v[142:145], v[66:69], v[198:201], 0
	v_mfma_i32_16x16x64_i8 v[130:133], v[106:109], v[198:201], 0
	v_mfma_i32_16x16x64_i8 v[134:137], v[66:69], v[214:217], 0
	v_mfma_i32_16x16x64_i8 v[122:125], v[106:109], v[214:217], 0
	v_mfma_i32_16x16x64_i8 v[154:157], v[70:73], v[186:189], v[154:157]
	v_mfma_i32_16x16x64_i8 v[146:149], v[110:113], v[186:189], v[146:149]
	v_mfma_i32_16x16x64_i8 v[150:153], v[70:73], v[194:197], v[150:153]
	v_mfma_i32_16x16x64_i8 v[138:141], v[110:113], v[194:197], v[138:141]
	v_mfma_i32_16x16x64_i8 v[142:145], v[70:73], v[210:213], v[142:145]
	v_mfma_i32_16x16x64_i8 v[130:133], v[110:113], v[210:213], v[130:133]
	v_mfma_i32_16x16x64_i8 v[134:137], v[70:73], v[218:221], v[134:137]
	v_mfma_i32_16x16x64_i8 v[122:125], v[110:113], v[218:221], v[122:125]
	s_setprio 0
	s_setprio 1
	v_mfma_i32_16x16x64_i8 v[102:105], v[114:117], v[182:185], 0
	v_mfma_i32_16x16x64_i8 v[94:97], v[126:129], v[182:185], 0
	v_mfma_i32_16x16x64_i8 v[98:101], v[114:117], v[190:193], 0
	v_mfma_i32_16x16x64_i8 v[86:89], v[126:129], v[190:193], 0
	v_mfma_i32_16x16x64_i8 v[90:93], v[114:117], v[198:201], 0
	v_mfma_i32_16x16x64_i8 v[78:81], v[126:129], v[198:201], 0
	v_mfma_i32_16x16x64_i8 v[82:85], v[114:117], v[214:217], 0
	v_mfma_i32_16x16x64_i8 v[74:77], v[126:129], v[214:217], 0
	v_mfma_i32_16x16x64_i8 v[102:105], v[118:121], v[186:189], v[102:105]
	v_mfma_i32_16x16x64_i8 v[94:97], v[178:181], v[186:189], v[94:97]
	v_mfma_i32_16x16x64_i8 v[98:101], v[118:121], v[194:197], v[98:101]
	v_mfma_i32_16x16x64_i8 v[86:89], v[178:181], v[194:197], v[86:89]
	v_mfma_i32_16x16x64_i8 v[90:93], v[118:121], v[210:213], v[90:93]
	v_mfma_i32_16x16x64_i8 v[78:81], v[178:181], v[210:213], v[78:81]
	v_mfma_i32_16x16x64_i8 v[82:85], v[118:121], v[218:221], v[82:85]
	v_mfma_i32_16x16x64_i8 v[74:77], v[178:181], v[218:221], v[74:77]
	s_setprio 0
	s_barrier
	s_add_i32 s8, s66, s81
	v_lshl_add_u64 v[168:169], s[96:97], 0, v[0:1]
	s_mov_b32 m0, s8
	ds_read_b128 v[182:185], v177 offset:16384
	ds_read_b128 v[186:189], v177 offset:17408
	ds_read_b128 v[190:193], v177 offset:18432
	ds_read_b128 v[194:197], v177 offset:19456
	ds_read_b128 v[198:201], v177 offset:20480
	ds_read_b128 v[210:213], v177 offset:21504
	ds_read_b128 v[214:217], v177 offset:22528
	ds_read_b128 v[218:221], v177 offset:23552
	global_load_lds_dwordx4 v[168:169], off
	s_add_i32 m0, s8, 0x2000
	s_add_u32 s8, s96, 0x40000
	v_lshl_add_u64 v[206:207], s[96:97], 0, v[158:159]
	s_addc_u32 s9, s97, 0
	s_add_i32 s66, s70, s81
	global_load_lds_dwordx4 v[206:207], off
	v_lshl_add_u64 v[222:223], s[8:9], 0, v[0:1]
	s_mov_b32 m0, s66
	v_lshl_add_u64 v[224:225], vcc, 0, v[160:161]
	global_load_lds_dwordx4 v[222:223], off
	v_lshl_add_u64 v[222:223], s[8:9], 0, v[158:159]
	s_add_i32 m0, s66, 0x2000
	s_nop 0
	global_load_lds_dwordx4 v[222:223], off
	v_lshl_add_u64 v[222:223], vcc, 0, v[162:163]
	s_mov_b32 m0, s1
	s_nop 0
	global_load_lds_dwordx4 v[222:223], off
	s_mov_b32 m0, s58
	s_nop 0
	global_load_lds_dwordx4 v[224:225], off
	s_waitcnt vmcnt(8)
	s_waitcnt lgkmcnt(0)
	s_barrier
; #define PG8_STAGE(bufoff, gbase, voff) do { _Pragma("unroll") for (int _i = 0; _i < 2; ++_i) \
;         __builtin_amdgcn_global_load_lds((const unsigned*)((const char*)(gbase) + (voff)[_i]), (PG8_LAS unsigned*)(lds + (bufoff) + ldsw + _i * 8192), 16, 0, 0); } while (0)
; #define PG8_LDA(dst, b, h) do { _Pragma("unroll") for (int m = 0; m < 4; ++m) _Pragma("unroll") for (int k = 0; k < 2; ++k) dst[m][k] = *(const PG8_LAS bf16x8*)(lds + PG8_SA(b, h) + aoff + m * 2048 + k * 1024); } while (0)
; #define PG8_LDB(dst, b, h) do { _Pragma("unroll") for (int n = 0; n < 2; ++n) _Pragma("unroll") for (int k = 0; k < 2; ++k) dst[n][k] = *(const PG8_LAS bf16x8*)(lds + PG8_SB(b, h) + boff + n * 2048 + k * 1024); } while (0)
; #define PG8_MMA(ai, bj, At, Bt) do { __builtin_amdgcn_s_setprio(1); _Pragma("unroll") for (int m = 0; m < 4; ++m) _Pragma("unroll") for (int n = 0; n < 2; ++n) _Pragma("unroll") for (int k = 0; k < 2; ++k) \
;         acc[ai][bj][m][n] = mma16<Epi::I8>(Bt[n][k], At[m][k], acc[ai][bj][m][n]); __builtin_amdgcn_s_setprio(0); } while (0)
; #define PG8_WAIT_V(n) asm volatile("s_waitcnt vmcnt(" #n ")" ::: "memory")
; #define PG8_WAIT_L(n) asm volatile("s_waitcnt lgkmcnt(" #n ")" ::: "memory")
; #define PG8_BAR __builtin_amdgcn_s_barrier()
; #define PG8_SCHED __builtin_amdgcn_sched_barrier(0)
; template <class Epi, class Sched, bool ALIGN_EPI = false, bool SP2 = false>
; __device__ __forceinline__ void gemm_phase(PG8_LAS unsigned char* lds, const Gemm g, const Sched& S, const Epi& E) {
;     ...
;             PG8_WAIT_V(8); PG8_WAIT_L(0); PG8_BAR; PG8_MMA(1, 0, At, B0); PG8_MMA(1, 1, At, B1); PG8_BAR; PG8_SCHED;
;             PG8_LDB(B0, 1, 0); PG8_LDB(B1, 1, 1); PG8_SCHED; PG8_LDA(At, 1, 0); PG8_STAGE(PG8_SA(0, 1), a2 + hstep, voffA);
;             PG8_WAIT_V(8); PG8_WAIT_L(0); PG8_BAR; PG8_MMA(0, 0, At, B0); PG8_MMA(0, 1, At, B1); PG8_BAR; PG8_SCHED;
	s_setprio 1
	s_waitcnt lgkmcnt(0)
	v_mfma_i32_16x16x64_i8 v[62:65], v[66:69], v[182:185], 0
	v_mfma_i32_16x16x64_i8 v[54:57], v[106:109], v[182:185], 0
	v_mfma_i32_16x16x64_i8 v[58:61], v[66:69], v[190:193], 0
	v_mfma_i32_16x16x64_i8 v[46:49], v[106:109], v[190:193], 0
	v_mfma_i32_16x16x64_i8 v[50:53], v[66:69], v[198:201], 0
	v_mfma_i32_16x16x64_i8 v[38:41], v[106:109], v[198:201], 0
	v_mfma_i32_16x16x64_i8 v[42:45], v[66:69], v[214:217], 0
	v_mfma_i32_16x16x64_i8 v[34:37], v[106:109], v[214:217], 0
	v_mfma_i32_16x16x64_i8 v[62:65], v[70:73], v[186:189], v[62:65]
	v_mfma_i32_16x16x64_i8 v[54:57], v[110:113], v[186:189], v[54:57]
	v_mfma_i32_16x16x64_i8 v[58:61], v[70:73], v[194:197], v[58:61]
	v_mfma_i32_16x16x64_i8 v[46:49], v[110:113], v[194:197], v[46:49]
	v_mfma_i32_16x16x64_i8 v[50:53], v[70:73], v[210:213], v[50:53]
	v_mfma_i32_16x16x64_i8 v[38:41], v[110:113], v[210:213], v[38:41]
	v_mfma_i32_16x16x64_i8 v[42:45], v[70:73], v[218:221], v[42:45]
	v_mfma_i32_16x16x64_i8 v[34:37], v[110:113], v[218:221], v[34:37]
	s_setprio 0
	s_setprio 1
	v_mfma_i32_16x16x64_i8 v[30:33], v[114:117], v[182:185], 0
	v_mfma_i32_16x16x64_i8 v[22:25], v[126:129], v[182:185], 0
	v_mfma_i32_16x16x64_i8 v[26:29], v[114:117], v[190:193], 0
	v_mfma_i32_16x16x64_i8 v[14:17], v[126:129], v[190:193], 0
	v_mfma_i32_16x16x64_i8 v[18:21], v[114:117], v[198:201], 0
	v_mfma_i32_16x16x64_i8 v[6:9], v[126:129], v[198:201], 0
	v_mfma_i32_16x16x64_i8 v[10:13], v[114:117], v[214:217], 0
	v_mfma_i32_16x16x64_i8 v[2:5], v[126:129], v[214:217], 0
	v_mfma_i32_16x16x64_i8 v[30:33], v[118:121], v[186:189], v[30:33]
	v_mfma_i32_16x16x64_i8 v[22:25], v[178:181], v[186:189], v[22:25]
	v_mfma_i32_16x16x64_i8 v[26:29], v[118:121], v[194:197], v[26:29]
	v_mfma_i32_16x16x64_i8 v[14:17], v[178:181], v[194:197], v[14:17]
	v_mfma_i32_16x16x64_i8 v[18:21], v[118:121], v[210:213], v[18:21]
	v_mfma_i32_16x16x64_i8 v[6:9], v[178:181], v[210:213], v[6:9]
	v_mfma_i32_16x16x64_i8 v[10:13], v[118:121], v[218:221], v[10:13]
	v_mfma_i32_16x16x64_i8 v[2:5], v[178:181], v[218:221], v[2:5]
	s_setprio 0
	s_barrier
	s_add_i32 s66, 0, 0x18000
	s_add_i32 s70, 0, 0x1c000
	v_add_u32_e32 v110, s66, v175
	v_add_u32_e32 v170, s70, v175
	ds_read_b128 v[66:69], v110
	ds_read_b128 v[70:73], v110 offset:1024
	ds_read_b128 v[106:109], v110 offset:2048
	ds_read_b128 v[110:113], v110 offset:3072
	ds_read_b128 v[114:117], v170
	ds_read_b128 v[118:121], v170 offset:1024
	ds_read_b128 v[126:129], v170 offset:2048
	ds_read_b128 v[178:181], v170 offset:3072
	s_add_u32 s8, vcc_lo, 0x40000
	s_addc_u32 s9, vcc_hi, 0
	s_mov_b32 m0, s80
	v_lshl_add_u64 v[226:227], s[8:9], 0, v[162:163]
	ds_read_b128 v[182:185], v177 offset:32768
	ds_read_b128 v[186:189], v177 offset:33792
	ds_read_b128 v[190:193], v177 offset:34816
	ds_read_b128 v[194:197], v177 offset:35840
	ds_read_b128 v[198:201], v177 offset:36864
	ds_read_b128 v[210:213], v177 offset:37888
	ds_read_b128 v[214:217], v177 offset:38912
	ds_read_b128 v[218:221], v177 offset:39936
	global_load_lds_dwordx4 v[226:227], off
	v_lshl_add_u64 v[226:227], s[8:9], 0, v[160:161]
	s_mov_b32 m0, s0
	s_nop 0
	global_load_lds_dwordx4 v[226:227], off
	s_waitcnt vmcnt(8)
	s_waitcnt lgkmcnt(0)
	s_barrier
	s_setprio 1
	s_waitcnt lgkmcnt(0)
	v_mfma_i32_16x16x64_i8 v[154:157], v[66:69], v[182:185], v[154:157]
	v_mfma_i32_16x16x64_i8 v[146:149], v[106:109], v[182:185], v[146:149]
	v_mfma_i32_16x16x64_i8 v[150:153], v[66:69], v[190:193], v[150:153]
	v_mfma_i32_16x16x64_i8 v[138:141], v[106:109], v[190:193], v[138:141]
	v_mfma_i32_16x16x64_i8 v[142:145], v[66:69], v[198:201], v[142:145]
	v_mfma_i32_16x16x64_i8 v[130:133], v[106:109], v[198:201], v[130:133]
	v_mfma_i32_16x16x64_i8 v[134:137], v[66:69], v[214:217], v[134:137]
	v_mfma_i32_16x16x64_i8 v[122:125], v[106:109], v[214:217], v[122:125]
	v_mfma_i32_16x16x64_i8 v[154:157], v[70:73], v[186:189], v[154:157]
	v_mfma_i32_16x16x64_i8 v[146:149], v[110:113], v[186:189], v[146:149]
	v_mfma_i32_16x16x64_i8 v[150:153], v[70:73], v[194:197], v[150:153]
	v_mfma_i32_16x16x64_i8 v[138:141], v[110:113], v[194:197], v[138:141]
	v_mfma_i32_16x16x64_i8 v[142:145], v[70:73], v[210:213], v[142:145]
	v_mfma_i32_16x16x64_i8 v[130:133], v[110:113], v[210:213], v[130:133]
	v_mfma_i32_16x16x64_i8 v[134:137], v[70:73], v[218:221], v[134:137]
	v_mfma_i32_16x16x64_i8 v[122:125], v[110:113], v[218:221], v[122:125]
	s_setprio 0
	s_setprio 1
	v_mfma_i32_16x16x64_i8 v[102:105], v[114:117], v[182:185], v[102:105]
	v_mfma_i32_16x16x64_i8 v[94:97], v[126:129], v[182:185], v[94:97]
	v_mfma_i32_16x16x64_i8 v[98:101], v[114:117], v[190:193], v[98:101]
	v_mfma_i32_16x16x64_i8 v[86:89], v[126:129], v[190:193], v[86:89]
	v_mfma_i32_16x16x64_i8 v[90:93], v[114:117], v[198:201], v[90:93]
	v_mfma_i32_16x16x64_i8 v[78:81], v[126:129], v[198:201], v[78:81]
	v_mfma_i32_16x16x64_i8 v[82:85], v[114:117], v[214:217], v[82:85]
	v_mfma_i32_16x16x64_i8 v[74:77], v[126:129], v[214:217], v[74:77]
	v_mfma_i32_16x16x64_i8 v[102:105], v[118:121], v[186:189], v[102:105]
	v_mfma_i32_16x16x64_i8 v[94:97], v[178:181], v[186:189], v[94:97]
	v_mfma_i32_16x16x64_i8 v[98:101], v[118:121], v[194:197], v[98:101]
	v_mfma_i32_16x16x64_i8 v[86:89], v[178:181], v[194:197], v[86:89]
	v_mfma_i32_16x16x64_i8 v[90:93], v[118:121], v[210:213], v[90:93]
	v_mfma_i32_16x16x64_i8 v[78:81], v[178:181], v[210:213], v[78:81]
	v_mfma_i32_16x16x64_i8 v[82:85], v[118:121], v[218:221], v[82:85]
	v_mfma_i32_16x16x64_i8 v[74:77], v[178:181], v[218:221], v[74:77]
	s_setprio 0
	s_barrier
; #define PG8_STAGE(bufoff, gbase, voff) do { _Pragma("unroll") for (int _i = 0; _i < 2; ++_i) \
;         __builtin_amdgcn_global_load_lds((const unsigned*)((const char*)(gbase) + (voff)[_i]), (PG8_LAS unsigned*)(lds + (bufoff) + ldsw + _i * 8192), 16, 0, 0); } while (0)
; #define PG8_LDA(dst, b, h) do { _Pragma("unroll") for (int m = 0; m < 4; ++m) _Pragma("unroll") for (int k = 0; k < 2; ++k) dst[m][k] = *(const PG8_LAS bf16x8*)(lds + PG8_SA(b, h) + aoff + m * 2048 + k * 1024); } while (0)
; #define PG8_MMA(ai, bj, At, Bt) do { __builtin_amdgcn_s_setprio(1); _Pragma("unroll") for (int m = 0; m < 4; ++m) _Pragma("unroll") for (int n = 0; n < 2; ++n) _Pragma("unroll") for (int k = 0; k < 2; ++k) \
;         acc[ai][bj][m][n] = mma16<Epi::I8>(Bt[n][k], At[m][k], acc[ai][bj][m][n]); __builtin_amdgcn_s_setprio(0); } while (0)
; #define PG8_WAIT_V(n) asm volatile("s_waitcnt vmcnt(" #n ")" ::: "memory")
; #define PG8_WAIT_L(n) asm volatile("s_waitcnt lgkmcnt(" #n ")" ::: "memory")
; #define PG8_BAR __builtin_amdgcn_s_barrier()
; #define PG8_SCHED __builtin_amdgcn_sched_barrier(0)
; template <class Epi, class Sched, bool ALIGN_EPI = false, bool SP2 = false>
; __device__ __forceinline__ void gemm_phase(PG8_LAS unsigned char* lds, const Gemm g, const Sched& S, const Epi& E) {
;     ...
;         for (int t = 0; t < nt; t += 2) {
;     ...
;             PG8_LDA(At, 1, 1); PG8_STAGE(PG8_SB(1, 0), b3, voffB); PG8_STAGE(PG8_SB(1, 1), b3 + hstep, voffB); PG8_STAGE(PG8_SA(1, 0), a3, voffA);
;             PG8_WAIT_V(8); PG8_WAIT_L(0); PG8_BAR; PG8_MMA(1, 0, At, B0); PG8_MMA(1, 1, At, B1); PG8_BAR; PG8_SCHED;
	s_add_i32 s8, s66, s81
	v_lshl_add_u64 v[168:169], v[168:169], 0, s[92:93]
	s_mov_b32 m0, s8
	ds_read_b128 v[182:185], v177 offset:49152
	ds_read_b128 v[186:189], v177 offset:50176
	ds_read_b128 v[190:193], v177 offset:51200
	ds_read_b128 v[194:197], v177 offset:52224
	ds_read_b128 v[198:201], v177 offset:53248
	ds_read_b128 v[210:213], v177 offset:54272
	ds_read_b128 v[214:217], v177 offset:55296
	ds_read_b128 v[218:221], v177 offset:56320
	global_load_lds_dwordx4 v[168:169], off
	s_add_i32 m0, s8, 0x2000
	s_add_u32 s8, s96, 0x40080
	v_lshl_add_u64 v[168:169], v[206:207], 0, s[92:93]
	s_addc_u32 s9, s97, 0
	s_add_i32 s66, s70, s81
	global_load_lds_dwordx4 v[168:169], off
	v_lshl_add_u64 v[168:169], s[8:9], 0, v[0:1]
	s_mov_b32 m0, s66
	s_nop 0
	global_load_lds_dwordx4 v[168:169], off
	v_lshl_add_u64 v[168:169], s[8:9], 0, v[158:159]
	s_add_i32 m0, s66, 0x2000
	s_nop 0
	global_load_lds_dwordx4 v[168:169], off
	v_lshl_add_u64 v[168:169], v[222:223], 0, s[92:93]
	s_mov_b32 m0, s13
	s_nop 0
	global_load_lds_dwordx4 v[168:169], off
	v_lshl_add_u64 v[168:169], v[224:225], 0, s[92:93]
	s_mov_b32 m0, s12
	s_nop 0
	global_load_lds_dwordx4 v[168:169], off
	s_waitcnt vmcnt(8)
	s_waitcnt lgkmcnt(0)
	s_barrier
	s_setprio 1
	s_waitcnt lgkmcnt(0)
	v_mfma_i32_16x16x64_i8 v[62:65], v[66:69], v[182:185], v[62:65]
	v_mfma_i32_16x16x64_i8 v[54:57], v[106:109], v[182:185], v[54:57]
	v_mfma_i32_16x16x64_i8 v[58:61], v[66:69], v[190:193], v[58:61]
	v_mfma_i32_16x16x64_i8 v[46:49], v[106:109], v[190:193], v[46:49]
	v_mfma_i32_16x16x64_i8 v[50:53], v[66:69], v[198:201], v[50:53]
	v_mfma_i32_16x16x64_i8 v[38:41], v[106:109], v[198:201], v[38:41]
	v_mfma_i32_16x16x64_i8 v[42:45], v[66:69], v[214:217], v[42:45]
	v_mfma_i32_16x16x64_i8 v[34:37], v[106:109], v[214:217], v[34:37]
	v_mfma_i32_16x16x64_i8 v[62:65], v[70:73], v[186:189], v[62:65]
	v_mfma_i32_16x16x64_i8 v[54:57], v[110:113], v[186:189], v[54:57]
	v_mfma_i32_16x16x64_i8 v[58:61], v[70:73], v[194:197], v[58:61]
	v_mfma_i32_16x16x64_i8 v[46:49], v[110:113], v[194:197], v[46:49]
	v_mfma_i32_16x16x64_i8 v[50:53], v[70:73], v[210:213], v[50:53]
	v_mfma_i32_16x16x64_i8 v[38:41], v[110:113], v[210:213], v[38:41]
	v_mfma_i32_16x16x64_i8 v[42:45], v[70:73], v[218:221], v[42:45]
	v_mfma_i32_16x16x64_i8 v[34:37], v[110:113], v[218:221], v[34:37]
	s_setprio 0
	s_setprio 1
	v_mfma_i32_16x16x64_i8 v[30:33], v[114:117], v[182:185], v[30:33]
	v_mfma_i32_16x16x64_i8 v[22:25], v[126:129], v[182:185], v[22:25]
	v_mfma_i32_16x16x64_i8 v[26:29], v[114:117], v[190:193], v[26:29]
	v_mfma_i32_16x16x64_i8 v[14:17], v[126:129], v[190:193], v[14:17]
	v_mfma_i32_16x16x64_i8 v[18:21], v[114:117], v[198:201], v[18:21]
	v_mfma_i32_16x16x64_i8 v[6:9], v[126:129], v[198:201], v[6:9]
	v_mfma_i32_16x16x64_i8 v[10:13], v[114:117], v[214:217], v[10:13]
	v_mfma_i32_16x16x64_i8 v[2:5], v[126:129], v[214:217], v[2:5]
	v_mfma_i32_16x16x64_i8 v[30:33], v[118:121], v[186:189], v[30:33]
	v_mfma_i32_16x16x64_i8 v[22:25], v[178:181], v[186:189], v[22:25]
	v_mfma_i32_16x16x64_i8 v[26:29], v[118:121], v[194:197], v[26:29]
	v_mfma_i32_16x16x64_i8 v[14:17], v[178:181], v[194:197], v[14:17]
	v_mfma_i32_16x16x64_i8 v[18:21], v[118:121], v[210:213], v[18:21]
	v_mfma_i32_16x16x64_i8 v[6:9], v[178:181], v[210:213], v[6:9]
	v_mfma_i32_16x16x64_i8 v[10:13], v[118:121], v[218:221], v[10:13]
	v_mfma_i32_16x16x64_i8 v[2:5], v[178:181], v[218:221], v[2:5]
	s_setprio 0
	s_barrier
	s_add_i32 s10, s10, 2
	s_add_u32 s69, s69, 0x100
	s_addc_u32 s68, s68, 0
	s_cmp_gt_u32 s10, 13
	s_mov_b64 s[8:9], s[84:85]
	s_cbranch_scc0 .LBB0_291
	s_branch .Lpeelx291

; #define PG8_BAR __builtin_amdgcn_s_barrier()
; template <class Epi, class Sched, bool ALIGN_EPI = false, bool SP2 = false>
; __device__ __forceinline__ void gemm_phase(PG8_LAS unsigned char* lds, const Gemm g, const Sched& S, const Epi& E) {
;     ...
;         if constexpr (ALIGN_EPI) { if (wr == 0) PG8_BAR; }
.Lpeelx291:
	s_and_b64 vcc, exec, s[48:49]
	s_cbranch_vccz .LBB0_294
	s_barrier

; #define PG8_STAGE(bufoff, gbase, voff) do { _Pragma("unroll") for (int _i = 0; _i < 2; ++_i) \
;         __builtin_amdgcn_global_load_lds((const unsigned*)((const char*)(gbase) + (voff)[_i]), (PG8_LAS unsigned*)(lds + (bufoff) + ldsw + _i * 8192), 16, 0, 0); } while (0)
; #define PG8_LDA(dst, b, h) do { _Pragma("unroll") for (int m = 0; m < 4; ++m) _Pragma("unroll") for (int k = 0; k < 2; ++k) dst[m][k] = *(const PG8_LAS bf16x8*)(lds + PG8_SA(b, h) + aoff + m * 2048 + k * 1024); } while (0)
; #define PG8_LDB(dst, b, h) do { _Pragma("unroll") for (int n = 0; n < 2; ++n) _Pragma("unroll") for (int k = 0; k < 2; ++k) dst[n][k] = *(const PG8_LAS bf16x8*)(lds + PG8_SB(b, h) + boff + n * 2048 + k * 1024); } while (0)
; #define PG8_MMA(ai, bj, At, Bt) do { __builtin_amdgcn_s_setprio(1); _Pragma("unroll") for (int m = 0; m < 4; ++m) _Pragma("unroll") for (int n = 0; n < 2; ++n) _Pragma("unroll") for (int k = 0; k < 2; ++k) \
;         acc[ai][bj][m][n] = mma16<Epi::I8>(Bt[n][k], At[m][k], acc[ai][bj][m][n]); __builtin_amdgcn_s_setprio(0); } while (0)
; #define PG8_WAIT_V(n) asm volatile("s_waitcnt vmcnt(" #n ")" ::: "memory")
; #define PG8_WAIT_L(n) asm volatile("s_waitcnt lgkmcnt(" #n ")" ::: "memory")
; #define PG8_BAR __builtin_amdgcn_s_barrier()
; #define PG8_SCHED __builtin_amdgcn_sched_barrier(0)
; template <class Epi, class Sched, bool ALIGN_EPI = false, bool SP2 = false>
; __device__ __forceinline__ void gemm_phase(PG8_LAS unsigned char* lds, const Gemm g, const Sched& S, const Epi& E) {
;     ...
;             PG8_LDB(B0, 0, 0); PG8_LDB(B1, 0, 1); PG8_SCHED; PG8_LDA(At, 0, 0); PG8_STAGE(PG8_SA(1, 1), a1 + hstep, voffA);
;             PG8_WAIT_V(8); PG8_WAIT_L(0); PG8_BAR; PG8_MMA(0, 0, At, B0); PG8_MMA(0, 1, At, B1); PG8_BAR; PG8_SCHED;
;             PG8_LDA(At, 0, 1); PG8_STAGE(PG8_SB(0, 0), b2, voffB); PG8_STAGE(PG8_SB(0, 1), b2 + hstep, voffB); PG8_STAGE(PG8_SA(0, 0), a2, voffA);
;             PG8_WAIT_V(8); PG8_WAIT_L(0); PG8_BAR; PG8_MMA(1, 0, At, B0); PG8_MMA(1, 1, At, B1); PG8_BAR; PG8_SCHED;
;     ...
;         for (int a = 0; a < 2; ++a)
; #pragma unroll
;             for (int b = 0; b < 2; ++b)
; #pragma unroll
;                 for (int m = 0; m < 4; ++m)
; #pragma unroll
;                     for (int n = 0; n < 2; ++n) acc[a][b][m][n] = (f32x4){0.f, 0.f, 0.f, 0.f};
;         cur = nxt; cA = nA; cB = nB; ++ui;
.LBB0_326:
	s_ashr_i32 s71, s70, 31
	s_lshl_b64 s[4:5], s[70:71], 20
	v_readlane_b32 s10, v252, 16
	v_readlane_b32 s11, v252, 17
	s_add_u32 s10, s10, s4
	s_addc_u32 s11, s11, s5
	s_and_b64 s[4:5], s[50:51], exec
	s_cselect_b32 s1, s11, s9
	s_cselect_b32 s5, s10, s8
	s_ashr_i32 s49, s48, 31
	s_mov_b32 s20, s70
	s_lshl_b64 s[70:71], s[48:49], 20
	s_add_u32 s82, s21, s70
	v_readlane_b32 s4, v254, 42
	s_addc_u32 s83, s4, s71
	s_and_b64 s[70:71], s[50:51], exec
	s_cselect_b32 s7, s83, s69
	s_cselect_b32 s85, s82, s68
	s_add_u32 s97, s68, 0x100
	s_waitcnt lgkmcnt(0)
	s_mov_b64 s[18:19], s[10:11]
	s_addc_u32 s96, s69, 0
	s_mov_b32 s4, -2
	s_waitcnt vmcnt(0)
.Lpeel327:
	s_add_u32 s68, s8, 0x100
	s_addc_u32 s69, s9, 0
	s_add_i32 s84, 0, 0x10000
	s_cmp_eq_u32 s4, 28
	s_cselect_b32 vcc_hi, s1, s69
	s_cselect_b32 vcc_lo, s5, s68
	v_add_u32_e32 v0, s84, v188
	s_cselect_b32 s71, s7, s96
	s_cselect_b32 s70, s85, s97
	s_add_i32 s10, 0, 0x14000
	ds_read_b128 v[52:55], v0
	ds_read_b128 v[56:59], v0 offset:1024
	ds_read_b128 v[76:79], v0 offset:2048
	ds_read_b128 v[80:83], v0 offset:3072
	v_add_u32_e32 v0, s10, v188
	ds_read_b128 v[116:119], v0
	ds_read_b128 v[120:123], v0 offset:1024
	ds_read_b128 v[168:171], v0 offset:2048
	ds_read_b128 v[172:175], v0 offset:3072
	v_lshl_add_u64 v[2:3], s[8:9], 0, v[164:165]
	s_add_i32 m0, s58, 0xc000
	ds_read_b128 v[176:179], v189
	ds_read_b128 v[180:183], v189 offset:1024
	ds_read_b128 v[190:193], v189 offset:2048
	ds_read_b128 v[194:197], v189 offset:3072
	ds_read_b128 v[198:201], v189 offset:4096
	ds_read_b128 v[210:213], v189 offset:5120
	ds_read_b128 v[214:217], v189 offset:6144
	ds_read_b128 v[218:221], v189 offset:7168
	global_load_lds_dwordx4 v[2:3], off
	v_lshl_add_u64 v[2:3], s[8:9], 0, v[166:167]
	s_add_i32 m0, s58, 0xe000
	s_nop 0
	global_load_lds_dwordx4 v[2:3], off
	s_waitcnt vmcnt(8)
	s_waitcnt lgkmcnt(0)
	s_barrier
	s_setprio 1
	s_waitcnt lgkmcnt(0)
	v_mfma_f32_16x16x32_bf16 v[152:155], v[52:55], v[176:179], 0
	v_mfma_f32_16x16x32_bf16 v[144:147], v[76:79], v[176:179], 0
	v_mfma_f32_16x16x32_bf16 v[148:151], v[52:55], v[190:193], 0
	v_mfma_f32_16x16x32_bf16 v[140:143], v[76:79], v[190:193], 0
	v_mfma_f32_16x16x32_bf16 v[136:139], v[52:55], v[198:201], 0
	v_mfma_f32_16x16x32_bf16 v[132:135], v[76:79], v[198:201], 0
	v_mfma_f32_16x16x32_bf16 v[128:131], v[52:55], v[214:217], 0
	v_mfma_f32_16x16x32_bf16 v[124:127], v[76:79], v[214:217], 0
	v_mfma_f32_16x16x32_bf16 v[152:155], v[56:59], v[180:183], v[152:155]
	v_mfma_f32_16x16x32_bf16 v[144:147], v[80:83], v[180:183], v[144:147]
	v_mfma_f32_16x16x32_bf16 v[148:151], v[56:59], v[194:197], v[148:151]
	v_mfma_f32_16x16x32_bf16 v[140:143], v[80:83], v[194:197], v[140:143]
	v_mfma_f32_16x16x32_bf16 v[136:139], v[56:59], v[210:213], v[136:139]
	v_mfma_f32_16x16x32_bf16 v[132:135], v[80:83], v[210:213], v[132:135]
	v_mfma_f32_16x16x32_bf16 v[128:131], v[56:59], v[218:221], v[128:131]
	v_mfma_f32_16x16x32_bf16 v[124:127], v[80:83], v[218:221], v[124:127]
	s_setprio 0
	s_setprio 1
	v_mfma_f32_16x16x32_bf16 v[112:115], v[116:119], v[176:179], 0
	v_mfma_f32_16x16x32_bf16 v[104:107], v[168:171], v[176:179], 0
	v_mfma_f32_16x16x32_bf16 v[108:111], v[116:119], v[190:193], 0
	v_mfma_f32_16x16x32_bf16 v[100:103], v[168:171], v[190:193], 0
	v_mfma_f32_16x16x32_bf16 v[96:99], v[116:119], v[198:201], 0
	v_mfma_f32_16x16x32_bf16 v[92:95], v[168:171], v[198:201], 0
	v_mfma_f32_16x16x32_bf16 v[88:91], v[116:119], v[214:217], 0
	v_mfma_f32_16x16x32_bf16 v[84:87], v[168:171], v[214:217], 0
	v_mfma_f32_16x16x32_bf16 v[112:115], v[120:123], v[180:183], v[112:115]
	v_mfma_f32_16x16x32_bf16 v[104:107], v[172:175], v[180:183], v[104:107]
	v_mfma_f32_16x16x32_bf16 v[108:111], v[120:123], v[194:197], v[108:111]
	v_mfma_f32_16x16x32_bf16 v[100:103], v[172:175], v[194:197], v[100:103]
	v_mfma_f32_16x16x32_bf16 v[96:99], v[120:123], v[210:213], v[96:99]
	v_mfma_f32_16x16x32_bf16 v[92:95], v[172:175], v[210:213], v[92:95]
	v_mfma_f32_16x16x32_bf16 v[88:91], v[120:123], v[218:221], v[88:91]
	v_mfma_f32_16x16x32_bf16 v[84:87], v[172:175], v[218:221], v[84:87]
	s_setprio 0
	s_barrier
	s_add_i32 s8, s84, s80
	v_lshl_add_u64 v[184:185], s[70:71], 0, v[158:159]
	s_mov_b32 m0, s8
	ds_read_b128 v[176:179], v189 offset:16384
	ds_read_b128 v[180:183], v189 offset:17408
	ds_read_b128 v[190:193], v189 offset:18432
	ds_read_b128 v[194:197], v189 offset:19456
	ds_read_b128 v[198:201], v189 offset:20480
	ds_read_b128 v[210:213], v189 offset:21504
	ds_read_b128 v[214:217], v189 offset:22528
	ds_read_b128 v[218:221], v189 offset:23552
	global_load_lds_dwordx4 v[184:185], off
	s_add_i32 m0, s8, 0x2000
	s_add_u32 s8, s70, 0x80000
	v_lshl_add_u64 v[206:207], s[70:71], 0, v[162:163]
	s_addc_u32 s9, s71, 0
	s_add_i32 s10, s10, s80
	global_load_lds_dwordx4 v[206:207], off
	v_lshl_add_u64 v[2:3], s[8:9], 0, v[158:159]
	s_mov_b32 m0, s10
	v_lshl_add_u64 v[222:223], vcc, 0, v[156:157]
	global_load_lds_dwordx4 v[2:3], off
	v_lshl_add_u64 v[2:3], s[8:9], 0, v[162:163]
	s_add_i32 m0, s10, 0x2000
	v_lshl_add_u64 v[224:225], vcc, 0, v[160:161]
	global_load_lds_dwordx4 v[2:3], off
	s_mov_b32 m0, s58
	s_nop 0
	global_load_lds_dwordx4 v[222:223], off
	s_mov_b32 m0, s12
	s_nop 0
	global_load_lds_dwordx4 v[224:225], off
	s_waitcnt vmcnt(8)
	s_waitcnt lgkmcnt(0)
	s_barrier
; #define PG8_STAGE(bufoff, gbase, voff) do { _Pragma("unroll") for (int _i = 0; _i < 2; ++_i) \
;         __builtin_amdgcn_global_load_lds((const unsigned*)((const char*)(gbase) + (voff)[_i]), (PG8_LAS unsigned*)(lds + (bufoff) + ldsw + _i * 8192), 16, 0, 0); } while (0)
; #define PG8_LDA(dst, b, h) do { _Pragma("unroll") for (int m = 0; m < 4; ++m) _Pragma("unroll") for (int k = 0; k < 2; ++k) dst[m][k] = *(const PG8_LAS bf16x8*)(lds + PG8_SA(b, h) + aoff + m * 2048 + k * 1024); } while (0)
; #define PG8_LDB(dst, b, h) do { _Pragma("unroll") for (int n = 0; n < 2; ++n) _Pragma("unroll") for (int k = 0; k < 2; ++k) dst[n][k] = *(const PG8_LAS bf16x8*)(lds + PG8_SB(b, h) + boff + n * 2048 + k * 1024); } while (0)
; #define PG8_MMA(ai, bj, At, Bt) do { __builtin_amdgcn_s_setprio(1); _Pragma("unroll") for (int m = 0; m < 4; ++m) _Pragma("unroll") for (int n = 0; n < 2; ++n) _Pragma("unroll") for (int k = 0; k < 2; ++k) \
;         acc[ai][bj][m][n] = mma16<Epi::I8>(Bt[n][k], At[m][k], acc[ai][bj][m][n]); __builtin_amdgcn_s_setprio(0); } while (0)
; #define PG8_WAIT_V(n) asm volatile("s_waitcnt vmcnt(" #n ")" ::: "memory")
; #define PG8_WAIT_L(n) asm volatile("s_waitcnt lgkmcnt(" #n ")" ::: "memory")
; #define PG8_BAR __builtin_amdgcn_s_barrier()
; #define PG8_SCHED __builtin_amdgcn_sched_barrier(0)
; template <class Epi, class Sched, bool ALIGN_EPI = false, bool SP2 = false>
; __device__ __forceinline__ void gemm_phase(PG8_LAS unsigned char* lds, const Gemm g, const Sched& S, const Epi& E) {
;     ...
;             PG8_WAIT_V(8); PG8_WAIT_L(0); PG8_BAR; PG8_MMA(1, 0, At, B0); PG8_MMA(1, 1, At, B1); PG8_BAR; PG8_SCHED;
;             PG8_LDB(B0, 1, 0); PG8_LDB(B1, 1, 1); PG8_SCHED; PG8_LDA(At, 1, 0); PG8_STAGE(PG8_SA(0, 1), a2 + hstep, voffA);
;             PG8_WAIT_V(8); PG8_WAIT_L(0); PG8_BAR; PG8_MMA(0, 0, At, B0); PG8_MMA(0, 1, At, B1); PG8_BAR; PG8_SCHED;
	s_setprio 1
	s_waitcnt lgkmcnt(0)
	v_mfma_f32_16x16x32_bf16 v[72:75], v[52:55], v[176:179], 0
	v_mfma_f32_16x16x32_bf16 v[64:67], v[76:79], v[176:179], 0
	v_mfma_f32_16x16x32_bf16 v[68:71], v[52:55], v[190:193], 0
	v_mfma_f32_16x16x32_bf16 v[60:63], v[76:79], v[190:193], 0
	v_mfma_f32_16x16x32_bf16 v[48:51], v[52:55], v[198:201], 0
	v_mfma_f32_16x16x32_bf16 v[44:47], v[76:79], v[198:201], 0
	v_mfma_f32_16x16x32_bf16 v[40:43], v[52:55], v[214:217], 0
	v_mfma_f32_16x16x32_bf16 v[36:39], v[76:79], v[214:217], 0
	v_mfma_f32_16x16x32_bf16 v[72:75], v[56:59], v[180:183], v[72:75]
	v_mfma_f32_16x16x32_bf16 v[64:67], v[80:83], v[180:183], v[64:67]
	v_mfma_f32_16x16x32_bf16 v[68:71], v[56:59], v[194:197], v[68:71]
	v_mfma_f32_16x16x32_bf16 v[60:63], v[80:83], v[194:197], v[60:63]
	v_mfma_f32_16x16x32_bf16 v[48:51], v[56:59], v[210:213], v[48:51]
	v_mfma_f32_16x16x32_bf16 v[44:47], v[80:83], v[210:213], v[44:47]
	v_mfma_f32_16x16x32_bf16 v[40:43], v[56:59], v[218:221], v[40:43]
	v_mfma_f32_16x16x32_bf16 v[36:39], v[80:83], v[218:221], v[36:39]
	s_setprio 0
	s_setprio 1
	v_mfma_f32_16x16x32_bf16 v[32:35], v[116:119], v[176:179], 0
	v_mfma_f32_16x16x32_bf16 v[24:27], v[168:171], v[176:179], 0
	v_mfma_f32_16x16x32_bf16 v[28:31], v[116:119], v[190:193], 0
	v_mfma_f32_16x16x32_bf16 v[20:23], v[168:171], v[190:193], 0
	v_mfma_f32_16x16x32_bf16 v[16:19], v[116:119], v[198:201], 0
	v_mfma_f32_16x16x32_bf16 v[12:15], v[168:171], v[198:201], 0
	v_mfma_f32_16x16x32_bf16 v[8:11], v[116:119], v[214:217], 0
	v_mfma_f32_16x16x32_bf16 v[2:5], v[168:171], v[214:217], 0
	v_mfma_f32_16x16x32_bf16 v[32:35], v[120:123], v[180:183], v[32:35]
	v_mfma_f32_16x16x32_bf16 v[24:27], v[172:175], v[180:183], v[24:27]
	v_mfma_f32_16x16x32_bf16 v[28:31], v[120:123], v[194:197], v[28:31]
	v_mfma_f32_16x16x32_bf16 v[20:23], v[172:175], v[194:197], v[20:23]
	v_mfma_f32_16x16x32_bf16 v[16:19], v[120:123], v[210:213], v[16:19]
	v_mfma_f32_16x16x32_bf16 v[12:15], v[172:175], v[210:213], v[12:15]
	v_mfma_f32_16x16x32_bf16 v[8:11], v[120:123], v[218:221], v[8:11]
	v_mfma_f32_16x16x32_bf16 v[2:5], v[172:175], v[218:221], v[2:5]
	s_setprio 0
	s_barrier
	s_add_i32 s10, 0, 0x18000
	v_add_u32_e32 v0, s10, v188
	s_add_i32 s11, 0, 0x1c000
	ds_read_b128 v[52:55], v0
	ds_read_b128 v[56:59], v0 offset:1024
	ds_read_b128 v[76:79], v0 offset:2048
	ds_read_b128 v[80:83], v0 offset:3072
	v_add_u32_e32 v0, s11, v188
	ds_read_b128 v[116:119], v0
	ds_read_b128 v[120:123], v0 offset:1024
	ds_read_b128 v[168:171], v0 offset:2048
	ds_read_b128 v[172:175], v0 offset:3072
	s_add_u32 s8, vcc_lo, 0x80000
	s_addc_u32 s9, vcc_hi, 0
	s_mov_b32 m0, s13
	v_lshl_add_u64 v[6:7], s[8:9], 0, v[156:157]
	ds_read_b128 v[176:179], v189 offset:32768
	ds_read_b128 v[180:183], v189 offset:33792
	ds_read_b128 v[190:193], v189 offset:34816
	ds_read_b128 v[194:197], v189 offset:35840
	ds_read_b128 v[198:201], v189 offset:36864
	ds_read_b128 v[210:213], v189 offset:37888
	ds_read_b128 v[214:217], v189 offset:38912
	ds_read_b128 v[218:221], v189 offset:39936
	global_load_lds_dwordx4 v[6:7], off
	v_lshl_add_u64 v[6:7], s[8:9], 0, v[160:161]
	s_mov_b32 m0, s66
	s_nop 0
	global_load_lds_dwordx4 v[6:7], off
	s_waitcnt vmcnt(8)
	s_waitcnt lgkmcnt(0)
	s_barrier
	s_setprio 1
	s_waitcnt lgkmcnt(0)
	v_mfma_f32_16x16x32_bf16 v[152:155], v[52:55], v[176:179], v[152:155]
	v_mfma_f32_16x16x32_bf16 v[144:147], v[76:79], v[176:179], v[144:147]
	v_mfma_f32_16x16x32_bf16 v[148:151], v[52:55], v[190:193], v[148:151]
	v_mfma_f32_16x16x32_bf16 v[140:143], v[76:79], v[190:193], v[140:143]
	v_mfma_f32_16x16x32_bf16 v[136:139], v[52:55], v[198:201], v[136:139]
	v_mfma_f32_16x16x32_bf16 v[132:135], v[76:79], v[198:201], v[132:135]
	v_mfma_f32_16x16x32_bf16 v[128:131], v[52:55], v[214:217], v[128:131]
	v_mfma_f32_16x16x32_bf16 v[124:127], v[76:79], v[214:217], v[124:127]
	v_mfma_f32_16x16x32_bf16 v[152:155], v[56:59], v[180:183], v[152:155]
	v_mfma_f32_16x16x32_bf16 v[144:147], v[80:83], v[180:183], v[144:147]
	v_mfma_f32_16x16x32_bf16 v[148:151], v[56:59], v[194:197], v[148:151]
	v_mfma_f32_16x16x32_bf16 v[140:143], v[80:83], v[194:197], v[140:143]
	v_mfma_f32_16x16x32_bf16 v[136:139], v[56:59], v[210:213], v[136:139]
	v_mfma_f32_16x16x32_bf16 v[132:135], v[80:83], v[210:213], v[132:135]
	v_mfma_f32_16x16x32_bf16 v[128:131], v[56:59], v[218:221], v[128:131]
	v_mfma_f32_16x16x32_bf16 v[124:127], v[80:83], v[218:221], v[124:127]
	s_setprio 0
	s_setprio 1
	v_mfma_f32_16x16x32_bf16 v[112:115], v[116:119], v[176:179], v[112:115]
	v_mfma_f32_16x16x32_bf16 v[104:107], v[168:171], v[176:179], v[104:107]
	v_mfma_f32_16x16x32_bf16 v[108:111], v[116:119], v[190:193], v[108:111]
	v_mfma_f32_16x16x32_bf16 v[100:103], v[168:171], v[190:193], v[100:103]
	v_mfma_f32_16x16x32_bf16 v[96:99], v[116:119], v[198:201], v[96:99]
	v_mfma_f32_16x16x32_bf16 v[92:95], v[168:171], v[198:201], v[92:95]
	v_mfma_f32_16x16x32_bf16 v[88:91], v[116:119], v[214:217], v[88:91]
	v_mfma_f32_16x16x32_bf16 v[84:87], v[168:171], v[214:217], v[84:87]
	v_mfma_f32_16x16x32_bf16 v[112:115], v[120:123], v[180:183], v[112:115]
	v_mfma_f32_16x16x32_bf16 v[104:107], v[172:175], v[180:183], v[104:107]
	v_mfma_f32_16x16x32_bf16 v[108:111], v[120:123], v[194:197], v[108:111]
	v_mfma_f32_16x16x32_bf16 v[100:103], v[172:175], v[194:197], v[100:103]
	v_mfma_f32_16x16x32_bf16 v[96:99], v[120:123], v[210:213], v[96:99]
	v_mfma_f32_16x16x32_bf16 v[92:95], v[172:175], v[210:213], v[92:95]
	v_mfma_f32_16x16x32_bf16 v[88:91], v[120:123], v[218:221], v[88:91]
	v_mfma_f32_16x16x32_bf16 v[84:87], v[172:175], v[218:221], v[84:87]
	s_setprio 0
	s_barrier
; #define PG8_STAGE(bufoff, gbase, voff) do { _Pragma("unroll") for (int _i = 0; _i < 2; ++_i) \
;         __builtin_amdgcn_global_load_lds((const unsigned*)((const char*)(gbase) + (voff)[_i]), (PG8_LAS unsigned*)(lds + (bufoff) + ldsw + _i * 8192), 16, 0, 0); } while (0)
; #define PG8_LDA(dst, b, h) do { _Pragma("unroll") for (int m = 0; m < 4; ++m) _Pragma("unroll") for (int k = 0; k < 2; ++k) dst[m][k] = *(const PG8_LAS bf16x8*)(lds + PG8_SA(b, h) + aoff + m * 2048 + k * 1024); } while (0)
; #define PG8_MMA(ai, bj, At, Bt) do { __builtin_amdgcn_s_setprio(1); _Pragma("unroll") for (int m = 0; m < 4; ++m) _Pragma("unroll") for (int n = 0; n < 2; ++n) _Pragma("unroll") for (int k = 0; k < 2; ++k) \
;         acc[ai][bj][m][n] = mma16<Epi::I8>(Bt[n][k], At[m][k], acc[ai][bj][m][n]); __builtin_amdgcn_s_setprio(0); } while (0)
; #define PG8_WAIT_V(n) asm volatile("s_waitcnt vmcnt(" #n ")" ::: "memory")
; #define PG8_WAIT_L(n) asm volatile("s_waitcnt lgkmcnt(" #n ")" ::: "memory")
; #define PG8_BAR __builtin_amdgcn_s_barrier()
; #define PG8_SCHED __builtin_amdgcn_sched_barrier(0)
; template <class Epi, class Sched, bool ALIGN_EPI = false, bool SP2 = false>
; __device__ __forceinline__ void gemm_phase(PG8_LAS unsigned char* lds, const Gemm g, const Sched& S, const Epi& E) {
;     ...
;         for (int t = 0; t < nt; t += 2) {
;     ...
;             PG8_LDA(At, 1, 1); PG8_STAGE(PG8_SB(1, 0), b3, voffB); PG8_STAGE(PG8_SB(1, 1), b3 + hstep, voffB); PG8_STAGE(PG8_SA(1, 0), a3, voffA);
;             PG8_WAIT_V(8); PG8_WAIT_L(0); PG8_BAR; PG8_MMA(1, 0, At, B0); PG8_MMA(1, 1, At, B1); PG8_BAR; PG8_SCHED;
	s_add_i32 s8, s10, s80
	v_lshl_add_u64 v[6:7], v[184:185], 0, s[92:93]
	s_mov_b32 m0, s8
	ds_read_b128 v[176:179], v189 offset:49152
	ds_read_b128 v[180:183], v189 offset:50176
	ds_read_b128 v[190:193], v189 offset:51200
	ds_read_b128 v[194:197], v189 offset:52224
	ds_read_b128 v[198:201], v189 offset:53248
	ds_read_b128 v[210:213], v189 offset:54272
	ds_read_b128 v[214:217], v189 offset:55296
	ds_read_b128 v[218:221], v189 offset:56320
	global_load_lds_dwordx4 v[6:7], off
	s_add_i32 m0, s8, 0x2000
	s_add_u32 s8, s70, 0x80080
	v_lshl_add_u64 v[6:7], v[206:207], 0, s[92:93]
	s_addc_u32 s9, s71, 0
	s_add_i32 s10, s11, s80
	global_load_lds_dwordx4 v[6:7], off
	v_lshl_add_u64 v[6:7], s[8:9], 0, v[158:159]
	s_mov_b32 m0, s10
	s_nop 0
	global_load_lds_dwordx4 v[6:7], off
	v_lshl_add_u64 v[6:7], s[8:9], 0, v[162:163]
	s_add_i32 m0, s10, 0x2000
	s_nop 0
	global_load_lds_dwordx4 v[6:7], off
	v_lshl_add_u64 v[6:7], v[222:223], 0, s[92:93]
	s_mov_b32 m0, s67
	s_nop 0
	global_load_lds_dwordx4 v[6:7], off
	v_lshl_add_u64 v[6:7], v[224:225], 0, s[92:93]
	s_mov_b32 m0, s81
	s_nop 0
	global_load_lds_dwordx4 v[6:7], off
	s_waitcnt vmcnt(8)
	s_waitcnt lgkmcnt(0)
	s_barrier
	s_setprio 1
	s_waitcnt lgkmcnt(0)
	v_mfma_f32_16x16x32_bf16 v[72:75], v[52:55], v[176:179], v[72:75]
	v_mfma_f32_16x16x32_bf16 v[64:67], v[76:79], v[176:179], v[64:67]
	v_mfma_f32_16x16x32_bf16 v[68:71], v[52:55], v[190:193], v[68:71]
	v_mfma_f32_16x16x32_bf16 v[60:63], v[76:79], v[190:193], v[60:63]
	v_mfma_f32_16x16x32_bf16 v[48:51], v[52:55], v[198:201], v[48:51]
	v_mfma_f32_16x16x32_bf16 v[44:47], v[76:79], v[198:201], v[44:47]
	v_mfma_f32_16x16x32_bf16 v[40:43], v[52:55], v[214:217], v[40:43]
	v_mfma_f32_16x16x32_bf16 v[36:39], v[76:79], v[214:217], v[36:39]
	v_mfma_f32_16x16x32_bf16 v[72:75], v[56:59], v[180:183], v[72:75]
	v_mfma_f32_16x16x32_bf16 v[64:67], v[80:83], v[180:183], v[64:67]
	v_mfma_f32_16x16x32_bf16 v[68:71], v[56:59], v[194:197], v[68:71]
	v_mfma_f32_16x16x32_bf16 v[60:63], v[80:83], v[194:197], v[60:63]
	v_mfma_f32_16x16x32_bf16 v[48:51], v[56:59], v[210:213], v[48:51]
	v_mfma_f32_16x16x32_bf16 v[44:47], v[80:83], v[210:213], v[44:47]
	v_mfma_f32_16x16x32_bf16 v[40:43], v[56:59], v[218:221], v[40:43]
	v_mfma_f32_16x16x32_bf16 v[36:39], v[80:83], v[218:221], v[36:39]
	s_setprio 0
	s_setprio 1
	v_mfma_f32_16x16x32_bf16 v[32:35], v[116:119], v[176:179], v[32:35]
	v_mfma_f32_16x16x32_bf16 v[24:27], v[168:171], v[176:179], v[24:27]
	v_mfma_f32_16x16x32_bf16 v[28:31], v[116:119], v[190:193], v[28:31]
	v_mfma_f32_16x16x32_bf16 v[20:23], v[168:171], v[190:193], v[20:23]
	v_mfma_f32_16x16x32_bf16 v[16:19], v[116:119], v[198:201], v[16:19]
	v_mfma_f32_16x16x32_bf16 v[12:15], v[168:171], v[198:201], v[12:15]
	v_mfma_f32_16x16x32_bf16 v[6:9], v[116:119], v[214:217], v[8:11]
	v_mfma_f32_16x16x32_bf16 v[2:5], v[168:171], v[214:217], v[2:5]
	v_mfma_f32_16x16x32_bf16 v[32:35], v[120:123], v[180:183], v[32:35]
	v_mfma_f32_16x16x32_bf16 v[24:27], v[172:175], v[180:183], v[24:27]
	v_mfma_f32_16x16x32_bf16 v[28:31], v[120:123], v[194:197], v[28:31]
	v_mfma_f32_16x16x32_bf16 v[20:23], v[172:175], v[194:197], v[20:23]
	v_mfma_f32_16x16x32_bf16 v[16:19], v[120:123], v[210:213], v[16:19]
	v_mfma_f32_16x16x32_bf16 v[12:15], v[172:175], v[210:213], v[12:15]
	v_mfma_f32_16x16x32_bf16 v[8:11], v[120:123], v[218:221], v[6:9]
	v_mfma_f32_16x16x32_bf16 v[4:7], v[172:175], v[218:221], v[2:5]
	s_setprio 0
	s_barrier
	s_add_i32 s4, s4, 2
	s_add_u32 s97, s97, 0x100
	s_addc_u32 s96, s96, 0
	s_cmp_gt_u32 s4, 29
	s_mov_b64 s[8:9], s[68:69]
	s_cbranch_scc0 .LBB0_327
	s_branch .Lpeelx327

; #define PG8_BAR __builtin_amdgcn_s_barrier()
; template <class Epi, class Sched, bool ALIGN_EPI = false, bool SP2 = false>
; __device__ __forceinline__ void gemm_phase(PG8_LAS unsigned char* lds, const Gemm g, const Sched& S, const Epi& E) {
;     ...
;         if constexpr (ALIGN_EPI) { if (wr == 0) PG8_BAR; }
.Lpeelx327:
	s_and_b64 vcc, exec, s[44:45]
	s_cbranch_vccz .LBB0_330
	s_barrier

; #define PG8_STAGE(bufoff, gbase, voff) do { _Pragma("unroll") for (int _i = 0; _i < 2; ++_i) \
;         __builtin_amdgcn_global_load_lds((const unsigned*)((const char*)(gbase) + (voff)[_i]), (PG8_LAS unsigned*)(lds + (bufoff) + ldsw + _i * 8192), 16, 0, 0); } while (0)
; #define PG8_LDA(dst, b, h) do { _Pragma("unroll") for (int m = 0; m < 4; ++m) _Pragma("unroll") for (int k = 0; k < 2; ++k) dst[m][k] = *(const PG8_LAS bf16x8*)(lds + PG8_SA(b, h) + aoff + m * 2048 + k * 1024); } while (0)
; #define PG8_LDB(dst, b, h) do { _Pragma("unroll") for (int n = 0; n < 2; ++n) _Pragma("unroll") for (int k = 0; k < 2; ++k) dst[n][k] = *(const PG8_LAS bf16x8*)(lds + PG8_SB(b, h) + boff + n * 2048 + k * 1024); } while (0)
; #define PG8_MMA(ai, bj, At, Bt) do { __builtin_amdgcn_s_setprio(1); _Pragma("unroll") for (int m = 0; m < 4; ++m) _Pragma("unroll") for (int n = 0; n < 2; ++n) _Pragma("unroll") for (int k = 0; k < 2; ++k) \
;         acc[ai][bj][m][n] = mma16<Epi::I8>(Bt[n][k], At[m][k], acc[ai][bj][m][n]); __builtin_amdgcn_s_setprio(0); } while (0)
; #define PG8_WAIT_V(n) asm volatile("s_waitcnt vmcnt(" #n ")" ::: "memory")
; #define PG8_WAIT_L(n) asm volatile("s_waitcnt lgkmcnt(" #n ")" ::: "memory")
; #define PG8_BAR __builtin_amdgcn_s_barrier()
; #define PG8_SCHED __builtin_amdgcn_sched_barrier(0)
; template <class Epi, class Sched, bool ALIGN_EPI = false, bool SP2 = false>
; __device__ __forceinline__ void gemm_phase(PG8_LAS unsigned char* lds, const Gemm g, const Sched& S, const Epi& E) {
;     ...
;             PG8_LDB(B0, 0, 0); PG8_LDB(B1, 0, 1); PG8_SCHED; PG8_LDA(At, 0, 0); PG8_STAGE(PG8_SA(1, 1), a1 + hstep, voffA);
;             PG8_WAIT_V(8); PG8_WAIT_L(0); PG8_BAR; PG8_MMA(0, 0, At, B0); PG8_MMA(0, 1, At, B1); PG8_BAR; PG8_SCHED;
;             PG8_LDA(At, 0, 1); PG8_STAGE(PG8_SB(0, 0), b2, voffB); PG8_STAGE(PG8_SB(0, 1), b2 + hstep, voffB); PG8_STAGE(PG8_SA(0, 0), a2, voffA);
;             PG8_WAIT_V(8); PG8_WAIT_L(0); PG8_BAR; PG8_MMA(1, 0, At, B0); PG8_MMA(1, 1, At, B1); PG8_BAR; PG8_SCHED;
;     ...
;         for (int a = 0; a < 2; ++a)
; #pragma unroll
;             for (int b = 0; b < 2; ++b)
; #pragma unroll
;                 for (int m = 0; m < 4; ++m)
; #pragma unroll
;                     for (int n = 0; n < 2; ++n) acc[a][b][m][n] = (f32x4){0.f, 0.f, 0.f, 0.f};
;         cur = nxt; cA = nA; cB = nB; ++ui;
.LBB0_384:
	s_ashr_i32 s49, s48, 31
	s_lshl_b64 s[10:11], s[48:49], 19
	v_readlane_b32 s16, v252, 41
	v_readlane_b32 s17, v252, 42
	s_add_u32 s50, s16, s10
	s_addc_u32 s51, s17, s11
	s_and_b64 s[68:69], s[46:47], exec
	s_cselect_b32 s1, s51, s9
	s_cselect_b32 s7, s50, s8
	s_ashr_i32 s45, s44, 31
	s_lshl_b64 s[68:69], s[44:45], 19
	v_readlane_b32 s5, v252, 35
	s_add_u32 s96, s5, s68
	v_readlane_b32 s5, v252, 36
	s_addc_u32 s97, s5, s69
	s_and_b64 s[68:69], s[46:47], exec
	s_cselect_b32 s69, s97, s71
	s_cselect_b32 s81, s96, s70
	s_add_u32 s85, s70, 0x100
	s_waitcnt lgkmcnt(0)
	s_addc_u32 s68, s71, 0
	s_mov_b32 s5, -2
	s_waitcnt vmcnt(0)
	s_mov_b32 s16, 0x800000
.Lpeel385:
	s_add_u32 s70, s8, 0x100
	s_addc_u32 s71, s9, 0
	s_add_i32 s84, 0, 0x10000
	s_cmp_eq_u32 s5, 12
	s_cselect_b32 vcc_hi, s1, s71
	s_cselect_b32 vcc_lo, s7, s70
	v_add_u32_e32 v0, s84, v214
	s_cselect_b32 s83, s69, s68
	s_cselect_b32 s82, s81, s85
	s_add_i32 s10, 0, 0x14000
	ds_read_b128 v[44:47], v0
	ds_read_b128 v[52:55], v0 offset:1024
	ds_read_b128 v[60:63], v0 offset:2048
	ds_read_b128 v[64:67], v0 offset:3072
	v_add_u32_e32 v0, s10, v214
	ds_read_b128 v[84:87], v0
	ds_read_b128 v[88:91], v0 offset:1024
	ds_read_b128 v[92:95], v0 offset:2048
	ds_read_b128 v[100:103], v0 offset:3072
	v_lshl_add_u64 v[2:3], s[8:9], 0, v[184:185]
	s_add_i32 m0, s13, 0xc000
	ds_read_b128 v[124:127], v215
	ds_read_b128 v[128:131], v215 offset:1024
	ds_read_b128 v[140:143], v215 offset:2048
	ds_read_b128 v[188:191], v215 offset:3072
	ds_read_b128 v[192:195], v215 offset:4096
	ds_read_b128 v[196:199], v215 offset:5120
	ds_read_b128 v[216:219], v215 offset:6144
	ds_read_b128 v[220:223], v215 offset:7168
	global_load_lds_dwordx4 v[2:3], off
	v_lshl_add_u64 v[2:3], s[8:9], 0, v[186:187]
	s_add_i32 m0, s13, 0xe000
	s_nop 0
	global_load_lds_dwordx4 v[2:3], off
	s_waitcnt vmcnt(8)
	s_waitcnt lgkmcnt(0)
	s_barrier
	s_setprio 1
	s_waitcnt lgkmcnt(0)
	v_mfma_i32_16x16x64_i8 v[172:175], v[44:47], v[124:127], 0
	v_mfma_i32_16x16x64_i8 v[164:167], v[60:63], v[124:127], 0
	v_mfma_i32_16x16x64_i8 v[168:171], v[44:47], v[140:143], 0
	v_mfma_i32_16x16x64_i8 v[160:163], v[60:63], v[140:143], 0
	v_mfma_i32_16x16x64_i8 v[156:159], v[44:47], v[192:195], 0
	v_mfma_i32_16x16x64_i8 v[152:155], v[60:63], v[192:195], 0
	v_mfma_i32_16x16x64_i8 v[148:151], v[44:47], v[216:219], 0
	v_mfma_i32_16x16x64_i8 v[144:147], v[60:63], v[216:219], 0
	v_mfma_i32_16x16x64_i8 v[172:175], v[52:55], v[128:131], v[172:175]
	v_mfma_i32_16x16x64_i8 v[164:167], v[64:67], v[128:131], v[164:167]
	v_mfma_i32_16x16x64_i8 v[168:171], v[52:55], v[188:191], v[168:171]
	v_mfma_i32_16x16x64_i8 v[160:163], v[64:67], v[188:191], v[160:163]
	v_mfma_i32_16x16x64_i8 v[156:159], v[52:55], v[196:199], v[156:159]
	v_mfma_i32_16x16x64_i8 v[152:155], v[64:67], v[196:199], v[152:155]
	v_mfma_i32_16x16x64_i8 v[148:151], v[52:55], v[220:223], v[148:151]
	v_mfma_i32_16x16x64_i8 v[144:147], v[64:67], v[220:223], v[144:147]
	s_setprio 0
	s_setprio 1
	v_mfma_i32_16x16x64_i8 v[136:139], v[84:87], v[124:127], 0
	v_mfma_i32_16x16x64_i8 v[120:123], v[92:95], v[124:127], 0
	v_mfma_i32_16x16x64_i8 v[116:119], v[92:95], v[140:143], 0
	v_mfma_i32_16x16x64_i8 v[112:115], v[84:87], v[192:195], 0
	v_mfma_i32_16x16x64_i8 v[108:111], v[92:95], v[192:195], 0
	v_mfma_i32_16x16x64_i8 v[104:107], v[84:87], v[216:219], 0
	v_mfma_i32_16x16x64_i8 v[96:99], v[92:95], v[216:219], 0
	v_mfma_i32_16x16x64_i8 v[136:139], v[88:91], v[128:131], v[136:139]
	v_mfma_i32_16x16x64_i8 v[120:123], v[100:103], v[128:131], v[120:123]
	v_mfma_i32_16x16x64_i8 v[124:127], v[84:87], v[140:143], 0
	v_mfma_i32_16x16x64_i8 v[116:119], v[100:103], v[188:191], v[116:119]
	v_mfma_i32_16x16x64_i8 v[112:115], v[88:91], v[196:199], v[112:115]
	v_mfma_i32_16x16x64_i8 v[108:111], v[100:103], v[196:199], v[108:111]
	v_mfma_i32_16x16x64_i8 v[104:107], v[88:91], v[220:223], v[104:107]
	v_mfma_i32_16x16x64_i8 v[96:99], v[100:103], v[220:223], v[96:99]
	v_mfma_i32_16x16x64_i8 v[124:127], v[88:91], v[188:191], v[124:127]
	s_setprio 0
	s_barrier
	s_add_i32 s8, s84, s12
	v_lshl_add_u64 v[200:201], s[82:83], 0, v[178:179]
	s_mov_b32 m0, s8
	ds_read_b128 v[128:131], v215 offset:16384
	ds_read_b128 v[132:135], v215 offset:17408
	ds_read_b128 v[140:143], v215 offset:18432
	ds_read_b128 v[188:191], v215 offset:19456
	ds_read_b128 v[192:195], v215 offset:20480
	ds_read_b128 v[196:199], v215 offset:21504
	ds_read_b128 v[216:219], v215 offset:22528
	ds_read_b128 v[220:223], v215 offset:23552
	global_load_lds_dwordx4 v[200:201], off
	s_add_i32 m0, s8, 0x2000
	s_add_u32 s8, s82, 0x40000
	v_lshl_add_u64 v[206:207], s[82:83], 0, v[182:183]
	s_addc_u32 s9, s83, 0
	s_add_i32 s10, s10, s12
	global_load_lds_dwordx4 v[206:207], off
	v_lshl_add_u64 v[2:3], s[8:9], 0, v[178:179]
	s_mov_b32 m0, s10
	v_lshl_add_u64 v[210:211], vcc, 0, v[176:177]
	global_load_lds_dwordx4 v[2:3], off
	v_lshl_add_u64 v[2:3], s[8:9], 0, v[182:183]
	s_add_i32 m0, s10, 0x2000
	v_lshl_add_u64 v[224:225], vcc, 0, v[180:181]
	global_load_lds_dwordx4 v[2:3], off
	s_mov_b32 m0, s13
	s_nop 0
	global_load_lds_dwordx4 v[210:211], off
	s_mov_b32 m0, s66
	s_nop 0
	global_load_lds_dwordx4 v[224:225], off
	s_waitcnt vmcnt(8)
	s_waitcnt lgkmcnt(0)
	s_barrier
; #define PG8_STAGE(bufoff, gbase, voff) do { _Pragma("unroll") for (int _i = 0; _i < 2; ++_i) \
;         __builtin_amdgcn_global_load_lds((const unsigned*)((const char*)(gbase) + (voff)[_i]), (PG8_LAS unsigned*)(lds + (bufoff) + ldsw + _i * 8192), 16, 0, 0); } while (0)
; #define PG8_LDA(dst, b, h) do { _Pragma("unroll") for (int m = 0; m < 4; ++m) _Pragma("unroll") for (int k = 0; k < 2; ++k) dst[m][k] = *(const PG8_LAS bf16x8*)(lds + PG8_SA(b, h) + aoff + m * 2048 + k * 1024); } while (0)
; #define PG8_LDB(dst, b, h) do { _Pragma("unroll") for (int n = 0; n < 2; ++n) _Pragma("unroll") for (int k = 0; k < 2; ++k) dst[n][k] = *(const PG8_LAS bf16x8*)(lds + PG8_SB(b, h) + boff + n * 2048 + k * 1024); } while (0)
; #define PG8_MMA(ai, bj, At, Bt) do { __builtin_amdgcn_s_setprio(1); _Pragma("unroll") for (int m = 0; m < 4; ++m) _Pragma("unroll") for (int n = 0; n < 2; ++n) _Pragma("unroll") for (int k = 0; k < 2; ++k) \
;         acc[ai][bj][m][n] = mma16<Epi::I8>(Bt[n][k], At[m][k], acc[ai][bj][m][n]); __builtin_amdgcn_s_setprio(0); } while (0)
; #define PG8_WAIT_V(n) asm volatile("s_waitcnt vmcnt(" #n ")" ::: "memory")
; #define PG8_WAIT_L(n) asm volatile("s_waitcnt lgkmcnt(" #n ")" ::: "memory")
; #define PG8_BAR __builtin_amdgcn_s_barrier()
; #define PG8_SCHED __builtin_amdgcn_sched_barrier(0)
; template <class Epi, class Sched, bool ALIGN_EPI = false, bool SP2 = false>
; __device__ __forceinline__ void gemm_phase(PG8_LAS unsigned char* lds, const Gemm g, const Sched& S, const Epi& E) {
;     ...
;             PG8_WAIT_V(8); PG8_WAIT_L(0); PG8_BAR; PG8_MMA(1, 0, At, B0); PG8_MMA(1, 1, At, B1); PG8_BAR; PG8_SCHED;
;             PG8_LDB(B0, 1, 0); PG8_LDB(B1, 1, 1); PG8_SCHED; PG8_LDA(At, 1, 0); PG8_STAGE(PG8_SA(0, 1), a2 + hstep, voffA);
;             PG8_WAIT_V(8); PG8_WAIT_L(0); PG8_BAR; PG8_MMA(0, 0, At, B0); PG8_MMA(0, 1, At, B1); PG8_BAR; PG8_SCHED;
	s_setprio 1
	s_waitcnt lgkmcnt(0)
	v_mfma_i32_16x16x64_i8 v[80:83], v[44:47], v[128:131], 0
	v_mfma_i32_16x16x64_i8 v[72:75], v[60:63], v[128:131], 0
	v_mfma_i32_16x16x64_i8 v[76:79], v[44:47], v[140:143], 0
	v_mfma_i32_16x16x64_i8 v[68:71], v[60:63], v[140:143], 0
	v_mfma_i32_16x16x64_i8 v[56:59], v[44:47], v[192:195], 0
	v_mfma_i32_16x16x64_i8 v[48:51], v[60:63], v[192:195], 0
	v_mfma_i32_16x16x64_i8 v[40:43], v[44:47], v[216:219], 0
	v_mfma_i32_16x16x64_i8 v[36:39], v[60:63], v[216:219], 0
	v_mfma_i32_16x16x64_i8 v[80:83], v[52:55], v[132:135], v[80:83]
	v_mfma_i32_16x16x64_i8 v[72:75], v[64:67], v[132:135], v[72:75]
	v_mfma_i32_16x16x64_i8 v[76:79], v[52:55], v[188:191], v[76:79]
	v_mfma_i32_16x16x64_i8 v[68:71], v[64:67], v[188:191], v[68:71]
	v_mfma_i32_16x16x64_i8 v[56:59], v[52:55], v[196:199], v[56:59]
	v_mfma_i32_16x16x64_i8 v[48:51], v[64:67], v[196:199], v[48:51]
	v_mfma_i32_16x16x64_i8 v[40:43], v[52:55], v[220:223], v[40:43]
	v_mfma_i32_16x16x64_i8 v[36:39], v[64:67], v[220:223], v[36:39]
	s_setprio 0
	s_setprio 1
	v_mfma_i32_16x16x64_i8 v[32:35], v[84:87], v[128:131], 0
	v_mfma_i32_16x16x64_i8 v[24:27], v[92:95], v[128:131], 0
	v_mfma_i32_16x16x64_i8 v[28:31], v[84:87], v[140:143], 0
	v_mfma_i32_16x16x64_i8 v[20:23], v[92:95], v[140:143], 0
	v_mfma_i32_16x16x64_i8 v[16:19], v[84:87], v[192:195], 0
	v_mfma_i32_16x16x64_i8 v[12:15], v[92:95], v[192:195], 0
	v_mfma_i32_16x16x64_i8 v[8:11], v[84:87], v[216:219], 0
	v_mfma_i32_16x16x64_i8 v[2:5], v[92:95], v[216:219], 0
	v_mfma_i32_16x16x64_i8 v[32:35], v[88:91], v[132:135], v[32:35]
	v_mfma_i32_16x16x64_i8 v[24:27], v[100:103], v[132:135], v[24:27]
	v_mfma_i32_16x16x64_i8 v[28:31], v[88:91], v[188:191], v[28:31]
	v_mfma_i32_16x16x64_i8 v[20:23], v[100:103], v[188:191], v[20:23]
	v_mfma_i32_16x16x64_i8 v[16:19], v[88:91], v[196:199], v[16:19]
	v_mfma_i32_16x16x64_i8 v[12:15], v[100:103], v[196:199], v[12:15]
	v_mfma_i32_16x16x64_i8 v[8:11], v[88:91], v[220:223], v[8:11]
	v_mfma_i32_16x16x64_i8 v[2:5], v[100:103], v[220:223], v[2:5]
	s_setprio 0
	s_barrier
	s_add_i32 s10, 0, 0x18000
	v_add_u32_e32 v0, s10, v214
	s_add_i32 s11, 0, 0x1c000
	ds_read_b128 v[44:47], v0
	ds_read_b128 v[52:55], v0 offset:1024
	ds_read_b128 v[60:63], v0 offset:2048
	ds_read_b128 v[64:67], v0 offset:3072
	v_add_u32_e32 v0, s11, v214
	ds_read_b128 v[84:87], v0
	ds_read_b128 v[88:91], v0 offset:1024
	ds_read_b128 v[92:95], v0 offset:2048
	ds_read_b128 v[100:103], v0 offset:3072
	s_add_u32 s8, vcc_lo, 0x40000
	s_addc_u32 s9, vcc_hi, 0
	s_mov_b32 m0, s67
	v_lshl_add_u64 v[6:7], s[8:9], 0, v[176:177]
	ds_read_b128 v[128:131], v215 offset:32768
	ds_read_b128 v[132:135], v215 offset:33792
	ds_read_b128 v[140:143], v215 offset:34816
	ds_read_b128 v[188:191], v215 offset:35840
	ds_read_b128 v[192:195], v215 offset:36864
	ds_read_b128 v[196:199], v215 offset:37888
	ds_read_b128 v[216:219], v215 offset:38912
	ds_read_b128 v[220:223], v215 offset:39936
	global_load_lds_dwordx4 v[6:7], off
	v_lshl_add_u64 v[6:7], s[8:9], 0, v[180:181]
	s_mov_b32 m0, s80
	s_nop 0
	global_load_lds_dwordx4 v[6:7], off
	s_waitcnt vmcnt(8)
	s_waitcnt lgkmcnt(0)
	s_barrier
	s_setprio 1
	s_waitcnt lgkmcnt(0)
	v_mfma_i32_16x16x64_i8 v[172:175], v[44:47], v[128:131], v[172:175]
	v_mfma_i32_16x16x64_i8 v[164:167], v[60:63], v[128:131], v[164:167]
	v_mfma_i32_16x16x64_i8 v[168:171], v[44:47], v[140:143], v[168:171]
	v_mfma_i32_16x16x64_i8 v[160:163], v[60:63], v[140:143], v[160:163]
	v_mfma_i32_16x16x64_i8 v[156:159], v[44:47], v[192:195], v[156:159]
	v_mfma_i32_16x16x64_i8 v[152:155], v[60:63], v[192:195], v[152:155]
	v_mfma_i32_16x16x64_i8 v[148:151], v[44:47], v[216:219], v[148:151]
	v_mfma_i32_16x16x64_i8 v[144:147], v[60:63], v[216:219], v[144:147]
	v_mfma_i32_16x16x64_i8 v[172:175], v[52:55], v[132:135], v[172:175]
	v_mfma_i32_16x16x64_i8 v[164:167], v[64:67], v[132:135], v[164:167]
	v_mfma_i32_16x16x64_i8 v[168:171], v[52:55], v[188:191], v[168:171]
	v_mfma_i32_16x16x64_i8 v[160:163], v[64:67], v[188:191], v[160:163]
	v_mfma_i32_16x16x64_i8 v[156:159], v[52:55], v[196:199], v[156:159]
	v_mfma_i32_16x16x64_i8 v[152:155], v[64:67], v[196:199], v[152:155]
	v_mfma_i32_16x16x64_i8 v[148:151], v[52:55], v[220:223], v[148:151]
	v_mfma_i32_16x16x64_i8 v[144:147], v[64:67], v[220:223], v[144:147]
	s_setprio 0
	s_setprio 1
	v_mfma_i32_16x16x64_i8 v[136:139], v[84:87], v[128:131], v[136:139]
	v_mfma_i32_16x16x64_i8 v[120:123], v[92:95], v[128:131], v[120:123]
	v_mfma_i32_16x16x64_i8 v[124:127], v[84:87], v[140:143], v[124:127]
	v_mfma_i32_16x16x64_i8 v[116:119], v[92:95], v[140:143], v[116:119]
	v_mfma_i32_16x16x64_i8 v[112:115], v[84:87], v[192:195], v[112:115]
	v_mfma_i32_16x16x64_i8 v[108:111], v[92:95], v[192:195], v[108:111]
	v_mfma_i32_16x16x64_i8 v[104:107], v[84:87], v[216:219], v[104:107]
	v_mfma_i32_16x16x64_i8 v[96:99], v[92:95], v[216:219], v[96:99]
	v_mfma_i32_16x16x64_i8 v[136:139], v[88:91], v[132:135], v[136:139]
	v_mfma_i32_16x16x64_i8 v[120:123], v[100:103], v[132:135], v[120:123]
	v_mfma_i32_16x16x64_i8 v[132:135], v[88:91], v[188:191], v[124:127]
	v_mfma_i32_16x16x64_i8 v[116:119], v[100:103], v[188:191], v[116:119]
	v_mfma_i32_16x16x64_i8 v[112:115], v[88:91], v[196:199], v[112:115]
	v_mfma_i32_16x16x64_i8 v[108:111], v[100:103], v[196:199], v[108:111]
	v_mfma_i32_16x16x64_i8 v[104:107], v[88:91], v[220:223], v[104:107]
	v_mfma_i32_16x16x64_i8 v[96:99], v[100:103], v[220:223], v[96:99]
	s_setprio 0
	s_barrier
; #define PG8_STAGE(bufoff, gbase, voff) do { _Pragma("unroll") for (int _i = 0; _i < 2; ++_i) \
;         __builtin_amdgcn_global_load_lds((const unsigned*)((const char*)(gbase) + (voff)[_i]), (PG8_LAS unsigned*)(lds + (bufoff) + ldsw + _i * 8192), 16, 0, 0); } while (0)
; #define PG8_LDA(dst, b, h) do { _Pragma("unroll") for (int m = 0; m < 4; ++m) _Pragma("unroll") for (int k = 0; k < 2; ++k) dst[m][k] = *(const PG8_LAS bf16x8*)(lds + PG8_SA(b, h) + aoff + m * 2048 + k * 1024); } while (0)
; #define PG8_MMA(ai, bj, At, Bt) do { __builtin_amdgcn_s_setprio(1); _Pragma("unroll") for (int m = 0; m < 4; ++m) _Pragma("unroll") for (int n = 0; n < 2; ++n) _Pragma("unroll") for (int k = 0; k < 2; ++k) \
;         acc[ai][bj][m][n] = mma16<Epi::I8>(Bt[n][k], At[m][k], acc[ai][bj][m][n]); __builtin_amdgcn_s_setprio(0); } while (0)
; #define PG8_WAIT_V(n) asm volatile("s_waitcnt vmcnt(" #n ")" ::: "memory")
; #define PG8_WAIT_L(n) asm volatile("s_waitcnt lgkmcnt(" #n ")" ::: "memory")
; #define PG8_BAR __builtin_amdgcn_s_barrier()
; #define PG8_SCHED __builtin_amdgcn_sched_barrier(0)
; template <class Epi, class Sched, bool ALIGN_EPI = false, bool SP2 = false>
; __device__ __forceinline__ void gemm_phase(PG8_LAS unsigned char* lds, const Gemm g, const Sched& S, const Epi& E) {
;     ...
;         for (int t = 0; t < nt; t += 2) {
;     ...
;             PG8_LDA(At, 1, 1); PG8_STAGE(PG8_SB(1, 0), b3, voffB); PG8_STAGE(PG8_SB(1, 1), b3 + hstep, voffB); PG8_STAGE(PG8_SA(1, 0), a3, voffA);
;             PG8_WAIT_V(8); PG8_WAIT_L(0); PG8_BAR; PG8_MMA(1, 0, At, B0); PG8_MMA(1, 1, At, B1); PG8_BAR; PG8_SCHED;
	s_add_i32 s8, s10, s12
	v_lshl_add_u64 v[6:7], v[200:201], 0, s[92:93]
	s_mov_b32 m0, s8
	ds_read_b128 v[124:127], v215 offset:49152
	ds_read_b128 v[128:131], v215 offset:50176
	ds_read_b128 v[140:143], v215 offset:51200
	ds_read_b128 v[188:191], v215 offset:52224
	ds_read_b128 v[192:195], v215 offset:53248
	ds_read_b128 v[196:199], v215 offset:54272
	ds_read_b128 v[216:219], v215 offset:55296
	ds_read_b128 v[220:223], v215 offset:56320
	global_load_lds_dwordx4 v[6:7], off
	s_add_i32 m0, s8, 0x2000
	s_add_u32 s8, s82, 0x40080
	v_lshl_add_u64 v[6:7], v[206:207], 0, s[92:93]
	s_addc_u32 s9, s83, 0
	s_add_i32 s10, s11, s12
	global_load_lds_dwordx4 v[6:7], off
	v_lshl_add_u64 v[6:7], s[8:9], 0, v[178:179]
	s_mov_b32 m0, s10
	s_nop 0
	global_load_lds_dwordx4 v[6:7], off
	v_lshl_add_u64 v[6:7], s[8:9], 0, v[182:183]
	s_add_i32 m0, s10, 0x2000
	s_nop 0
	global_load_lds_dwordx4 v[6:7], off
	v_lshl_add_u64 v[6:7], v[210:211], 0, s[92:93]
	s_mov_b32 m0, s58
	s_nop 0
	global_load_lds_dwordx4 v[6:7], off
	v_lshl_add_u64 v[6:7], v[224:225], 0, s[92:93]
	s_mov_b32 m0, s4
	s_nop 0
	global_load_lds_dwordx4 v[6:7], off
	s_waitcnt vmcnt(8)
	s_waitcnt lgkmcnt(0)
	s_barrier
	s_setprio 1
	s_waitcnt lgkmcnt(0)
	v_mfma_i32_16x16x64_i8 v[80:83], v[44:47], v[124:127], v[80:83]
	v_mfma_i32_16x16x64_i8 v[72:75], v[60:63], v[124:127], v[72:75]
	v_mfma_i32_16x16x64_i8 v[76:79], v[44:47], v[140:143], v[76:79]
	v_mfma_i32_16x16x64_i8 v[68:71], v[60:63], v[140:143], v[68:71]
	v_mfma_i32_16x16x64_i8 v[56:59], v[44:47], v[192:195], v[56:59]
	v_mfma_i32_16x16x64_i8 v[48:51], v[60:63], v[192:195], v[48:51]
	v_mfma_i32_16x16x64_i8 v[40:43], v[44:47], v[216:219], v[40:43]
	v_mfma_i32_16x16x64_i8 v[36:39], v[60:63], v[216:219], v[36:39]
	v_mfma_i32_16x16x64_i8 v[80:83], v[52:55], v[128:131], v[80:83]
	v_mfma_i32_16x16x64_i8 v[72:75], v[64:67], v[128:131], v[72:75]
	v_mfma_i32_16x16x64_i8 v[76:79], v[52:55], v[188:191], v[76:79]
	v_mfma_i32_16x16x64_i8 v[68:71], v[64:67], v[188:191], v[68:71]
	v_mfma_i32_16x16x64_i8 v[56:59], v[52:55], v[196:199], v[56:59]
	v_mfma_i32_16x16x64_i8 v[48:51], v[64:67], v[196:199], v[48:51]
	v_mfma_i32_16x16x64_i8 v[40:43], v[52:55], v[220:223], v[40:43]
	v_mfma_i32_16x16x64_i8 v[36:39], v[64:67], v[220:223], v[36:39]
	s_setprio 0
	s_setprio 1
	v_mfma_i32_16x16x64_i8 v[32:35], v[84:87], v[124:127], v[32:35]
	v_mfma_i32_16x16x64_i8 v[24:27], v[92:95], v[124:127], v[24:27]
	v_mfma_i32_16x16x64_i8 v[28:31], v[84:87], v[140:143], v[28:31]
	v_mfma_i32_16x16x64_i8 v[20:23], v[92:95], v[140:143], v[20:23]
	v_mfma_i32_16x16x64_i8 v[16:19], v[84:87], v[192:195], v[16:19]
	v_mfma_i32_16x16x64_i8 v[12:15], v[92:95], v[192:195], v[12:15]
	v_mfma_i32_16x16x64_i8 v[6:9], v[84:87], v[216:219], v[8:11]
	v_mfma_i32_16x16x64_i8 v[2:5], v[92:95], v[216:219], v[2:5]
	v_mfma_i32_16x16x64_i8 v[32:35], v[88:91], v[128:131], v[32:35]
	v_mfma_i32_16x16x64_i8 v[24:27], v[100:103], v[128:131], v[24:27]
	v_mfma_i32_16x16x64_i8 v[28:31], v[88:91], v[188:191], v[28:31]
	v_mfma_i32_16x16x64_i8 v[20:23], v[100:103], v[188:191], v[20:23]
	v_mfma_i32_16x16x64_i8 v[16:19], v[88:91], v[196:199], v[16:19]
	v_mfma_i32_16x16x64_i8 v[12:15], v[100:103], v[196:199], v[12:15]
	v_mfma_i32_16x16x64_i8 v[8:11], v[88:91], v[220:223], v[6:9]
	v_mfma_i32_16x16x64_i8 v[4:7], v[100:103], v[220:223], v[2:5]
	s_setprio 0
	s_barrier
	s_add_i32 s5, s5, 2
	s_add_u32 s85, s85, 0x100
	s_addc_u32 s68, s68, 0
	s_cmp_gt_u32 s5, 13
	s_mov_b64 s[8:9], s[70:71]
	s_cbranch_scc0 .LBB0_385
	s_branch .Lpeelx385

; #define PG8_BAR __builtin_amdgcn_s_barrier()
; template <class Epi, class Sched, bool ALIGN_EPI = false, bool SP2 = false>
; __device__ __forceinline__ void gemm_phase(PG8_LAS unsigned char* lds, const Gemm g, const Sched& S, const Epi& E) {
;     ...
;         if constexpr (ALIGN_EPI) { if (wr == 0) PG8_BAR; }
.Lpeelx385:
	s_and_b64 vcc, exec, s[40:41]
	s_cbranch_vccz .LBB0_388
	s_barrier
